# GEMM K-loops: s_setprio 1 before the pre-MFMA barrier and s_setprio 0 after the post-MFMA barrier (shorter role-switch path)
# speedup vs baseline: 1.0227x; 1.0039x over previous
; #define PG8_STAGE(bufoff, gbase, voff) do { _Pragma("unroll") for (int _i = 0; _i < 2; ++_i) \
;         __builtin_amdgcn_global_load_lds((const unsigned*)((const char*)(gbase) + (voff)[_i]), (PG8_LAS unsigned*)(lds + (bufoff) + ldsw + _i * 8192), 16, 0, 0); } while (0)
; #define PG8_LDA(dst, b, h) do { _Pragma("unroll") for (int m = 0; m < 4; ++m) _Pragma("unroll") for (int k = 0; k < 2; ++k) dst[m][k] = *(const PG8_LAS bf16x8*)(lds + PG8_SA(b, h) + aoff + m * 2048 + k * 1024); } while (0)
; #define PG8_LDB(dst, b, h) do { _Pragma("unroll") for (int n = 0; n < 2; ++n) _Pragma("unroll") for (int k = 0; k < 2; ++k) dst[n][k] = *(const PG8_LAS bf16x8*)(lds + PG8_SB(b, h) + boff + n * 2048 + k * 1024); } while (0)
; #define PG8_MMA(ai, bj, At, Bt) do { __builtin_amdgcn_s_setprio(1); _Pragma("unroll") for (int m = 0; m < 4; ++m) _Pragma("unroll") for (int n = 0; n < 2; ++n) _Pragma("unroll") for (int k = 0; k < 2; ++k) \
;         acc[ai][bj][m][n] = __builtin_amdgcn_mfma_f32_16x16x32_bf16(Bt[n][k], At[m][k], acc[ai][bj][m][n], 0, 0, 0); __builtin_amdgcn_s_setprio(0); } while (0)
; #define PG8_WAIT_V(n) asm volatile("s_waitcnt vmcnt(" #n ")" ::: "memory")
; #define PG8_WAIT_L(n) asm volatile("s_waitcnt lgkmcnt(" #n ")" ::: "memory")
; template <class Epi, class Sched, bool ALIGN_EPI = false, bool SP2 = false>
; __device__ __forceinline__ void gemm_phase(PG8_LAS unsigned char* lds, const Gemm g, const Sched& S, const Epi& E) {
;     ...
;             const bool last = (t == nt - 2);
;             const char* a1 = cA + (size_t)(t + 1) * kstep;
;             const char* a2 = last ? nA : cA + (size_t)(t + 2) * kstep; const char* b2 = last ? nB : cB + (size_t)(t + 2) * kstep;
;             const char* a3 = a2 + kstep; const char* b3 = b2 + kstep;
;             if (last && has_next) S.a_ready(nxt);
;             if constexpr (SP2) {
;             PG8_LDB(B0, 0, 0); PG8_LDB(B1, 0, 1); PG8_SCHED; PG8_LDA(At, 0, 0); PG8_STAGE(PG8_SA(1, 1), a1 + hstep, voffA);
;             PG8_WAIT_V(8); PG8_WAIT_L(0); PG8_BAR; PG8_MMA(0, 0, At, B0); PG8_MMA(0, 1, At, B1); PG8_BAR; PG8_SCHED;
;             PG8_LDA(At, 0, 1); PG8_STAGE(PG8_SB(0, 0), b2, voffB); PG8_STAGE(PG8_SB(0, 1), b2 + hstep, voffB); PG8_STAGE(PG8_SA(0, 0), a2, voffA);
;             PG8_WAIT_V(8); PG8_WAIT_L(0); PG8_BAR; PG8_MMA(1, 0, At, B0); PG8_MMA(1, 1, At, B1); PG8_BAR; PG8_SCHED;
.LBB0_132:
	s_add_u32 s18, s46, 0xfffc0080
	s_addc_u32 s38, s47, -1
	s_add_i32 s39, 0, 0x10000
	s_cmp_eq_u32 s85, 12
	s_cselect_b32 s81, s33, s38
	s_cselect_b32 s80, s73, s18
	v_add_u32_e32 v0, s39, v176
	s_cselect_b32 s45, s75, s84
	s_cselect_b32 s44, s82, s83
	s_add_i32 s18, 0, 0x14000
	ds_read_b128 v[144:147], v0
	ds_read_b128 v[148:151], v0 offset:1024
	ds_read_b128 v[152:155], v0 offset:2048
	ds_read_b128 v[156:159], v0 offset:3072
	v_add_u32_e32 v0, s18, v176
	ds_read_b128 v[160:163], v0
	ds_read_b128 v[164:167], v0 offset:1024
	ds_read_b128 v[168:171], v0 offset:2048
	ds_read_b128 v[172:175], v0 offset:3072
	v_lshl_add_u64 v[218:219], s[46:47], 0, v[140:141]
	s_add_i32 m0, s92, 0xc000
	ds_read_b128 v[180:183], v178
	ds_read_b128 v[184:187], v178 offset:1024
	ds_read_b128 v[188:191], v178 offset:2048
	ds_read_b128 v[192:195], v178 offset:3072
	ds_read_b128 v[202:205], v178 offset:4096
	ds_read_b128 v[206:209], v178 offset:5120
	ds_read_b128 v[210:213], v178 offset:6144
	ds_read_b128 v[214:217], v178 offset:7168
	global_load_lds_dwordx4 v[218:219], off
	v_lshl_add_u64 v[218:219], s[46:47], 0, v[142:143]
	s_add_i32 m0, s92, 0xe000
	s_nop 0
	global_load_lds_dwordx4 v[218:219], off
	s_waitcnt vmcnt(8)
	s_waitcnt lgkmcnt(0)
	s_setprio 1
	s_barrier
	v_mfma_f32_16x16x32_bf16 v[118:121], v[144:147], v[180:183], v[118:121]
	v_mfma_f32_16x16x32_bf16 v[118:121], v[148:151], v[184:187], v[118:121]
	v_mfma_f32_16x16x32_bf16 v[102:105], v[144:147], v[188:191], v[102:105]
	v_mfma_f32_16x16x32_bf16 v[102:105], v[148:151], v[192:195], v[102:105]
	v_mfma_f32_16x16x32_bf16 v[86:89], v[144:147], v[202:205], v[86:89]
	v_mfma_f32_16x16x32_bf16 v[86:89], v[148:151], v[206:209], v[86:89]
	v_mfma_f32_16x16x32_bf16 v[70:73], v[144:147], v[210:213], v[70:73]
	v_mfma_f32_16x16x32_bf16 v[70:73], v[148:151], v[214:217], v[70:73]
	v_mfma_f32_16x16x32_bf16 v[114:117], v[152:155], v[180:183], v[114:117]
	v_mfma_f32_16x16x32_bf16 v[114:117], v[156:159], v[184:187], v[114:117]
	v_mfma_f32_16x16x32_bf16 v[98:101], v[152:155], v[188:191], v[98:101]
	v_mfma_f32_16x16x32_bf16 v[98:101], v[156:159], v[192:195], v[98:101]
	v_mfma_f32_16x16x32_bf16 v[82:85], v[152:155], v[202:205], v[82:85]
	v_mfma_f32_16x16x32_bf16 v[82:85], v[156:159], v[206:209], v[82:85]
	v_mfma_f32_16x16x32_bf16 v[66:69], v[152:155], v[210:213], v[66:69]
	v_mfma_f32_16x16x32_bf16 v[66:69], v[156:159], v[214:217], v[66:69]
	v_mfma_f32_16x16x32_bf16 v[126:129], v[160:163], v[180:183], v[126:129]
	v_mfma_f32_16x16x32_bf16 v[126:129], v[164:167], v[184:187], v[126:129]
	v_mfma_f32_16x16x32_bf16 v[110:113], v[160:163], v[188:191], v[110:113]
	v_mfma_f32_16x16x32_bf16 v[110:113], v[164:167], v[192:195], v[110:113]
	v_mfma_f32_16x16x32_bf16 v[94:97], v[160:163], v[202:205], v[94:97]
	v_mfma_f32_16x16x32_bf16 v[94:97], v[164:167], v[206:209], v[94:97]
	v_mfma_f32_16x16x32_bf16 v[78:81], v[160:163], v[210:213], v[78:81]
	v_mfma_f32_16x16x32_bf16 v[78:81], v[164:167], v[214:217], v[78:81]
	v_mfma_f32_16x16x32_bf16 v[122:125], v[168:171], v[180:183], v[122:125]
	v_mfma_f32_16x16x32_bf16 v[122:125], v[172:175], v[184:187], v[122:125]
	v_mfma_f32_16x16x32_bf16 v[106:109], v[168:171], v[188:191], v[106:109]
	v_mfma_f32_16x16x32_bf16 v[106:109], v[172:175], v[192:195], v[106:109]
	v_mfma_f32_16x16x32_bf16 v[90:93], v[168:171], v[202:205], v[90:93]
	v_mfma_f32_16x16x32_bf16 v[90:93], v[172:175], v[206:209], v[90:93]
	v_mfma_f32_16x16x32_bf16 v[74:77], v[168:171], v[210:213], v[74:77]
	v_mfma_f32_16x16x32_bf16 v[74:77], v[172:175], v[214:217], v[74:77]
	s_barrier
	s_setprio 0
	s_add_i32 s38, s39, s91
	v_lshl_add_u64 v[218:219], s[44:45], 0, v[134:135]
	s_mov_b32 m0, s38
	ds_read_b128 v[180:183], v178 offset:16384
	ds_read_b128 v[184:187], v178 offset:17408
	ds_read_b128 v[188:191], v178 offset:18432
	ds_read_b128 v[192:195], v178 offset:19456
	ds_read_b128 v[202:205], v178 offset:20480
	ds_read_b128 v[206:209], v178 offset:21504
	ds_read_b128 v[210:213], v178 offset:22528
	ds_read_b128 v[214:217], v178 offset:23552
	global_load_lds_dwordx4 v[218:219], off
	s_add_i32 m0, s38, 0x2000
	s_add_u32 s38, s44, 0x40000
	v_lshl_add_u64 v[220:221], s[44:45], 0, v[130:131]
	s_addc_u32 s39, s45, 0
	s_add_i32 s18, s18, s91
	global_load_lds_dwordx4 v[220:221], off
	v_lshl_add_u64 v[222:223], s[38:39], 0, v[134:135]
	s_mov_b32 m0, s18
	v_lshl_add_u64 v[224:225], s[80:81], 0, v[132:133]
	global_load_lds_dwordx4 v[222:223], off
	v_lshl_add_u64 v[222:223], s[38:39], 0, v[130:131]
	s_add_i32 m0, s18, 0x2000
	s_nop 0
	global_load_lds_dwordx4 v[222:223], off
	v_lshl_add_u64 v[222:223], s[80:81], 0, v[136:137]
	s_mov_b32 m0, s92
	s_nop 0
	global_load_lds_dwordx4 v[222:223], off
	s_mov_b32 m0, s93
	s_nop 0
	global_load_lds_dwordx4 v[224:225], off
	s_waitcnt vmcnt(8)
	s_waitcnt lgkmcnt(0)
	s_setprio 1
	s_barrier
; #define PG8_STAGE(bufoff, gbase, voff) do { _Pragma("unroll") for (int _i = 0; _i < 2; ++_i) \
;         __builtin_amdgcn_global_load_lds((const unsigned*)((const char*)(gbase) + (voff)[_i]), (PG8_LAS unsigned*)(lds + (bufoff) + ldsw + _i * 8192), 16, 0, 0); } while (0)
; #define PG8_LDA(dst, b, h) do { _Pragma("unroll") for (int m = 0; m < 4; ++m) _Pragma("unroll") for (int k = 0; k < 2; ++k) dst[m][k] = *(const PG8_LAS bf16x8*)(lds + PG8_SA(b, h) + aoff + m * 2048 + k * 1024); } while (0)
; #define PG8_LDB(dst, b, h) do { _Pragma("unroll") for (int n = 0; n < 2; ++n) _Pragma("unroll") for (int k = 0; k < 2; ++k) dst[n][k] = *(const PG8_LAS bf16x8*)(lds + PG8_SB(b, h) + boff + n * 2048 + k * 1024); } while (0)
; #define PG8_MMA(ai, bj, At, Bt) do { __builtin_amdgcn_s_setprio(1); _Pragma("unroll") for (int m = 0; m < 4; ++m) _Pragma("unroll") for (int n = 0; n < 2; ++n) _Pragma("unroll") for (int k = 0; k < 2; ++k) \
;         acc[ai][bj][m][n] = __builtin_amdgcn_mfma_f32_16x16x32_bf16(Bt[n][k], At[m][k], acc[ai][bj][m][n], 0, 0, 0); __builtin_amdgcn_s_setprio(0); } while (0)
; #define PG8_WAIT_V(n) asm volatile("s_waitcnt vmcnt(" #n ")" ::: "memory")
; #define PG8_WAIT_L(n) asm volatile("s_waitcnt lgkmcnt(" #n ")" ::: "memory")
; #define PG8_BAR __builtin_amdgcn_s_barrier()
; #define PG8_SCHED __builtin_amdgcn_sched_barrier(0)
; template <class Epi, class Sched, bool ALIGN_EPI = false, bool SP2 = false>
; __device__ __forceinline__ void gemm_phase(PG8_LAS unsigned char* lds, const Gemm g, const Sched& S, const Epi& E) {
;     ...
;             PG8_WAIT_V(8); PG8_WAIT_L(0); PG8_BAR; PG8_MMA(1, 0, At, B0); PG8_MMA(1, 1, At, B1); PG8_BAR; PG8_SCHED;
;             PG8_LDB(B0, 1, 0); PG8_LDB(B1, 1, 1); PG8_SCHED; PG8_LDA(At, 1, 0); PG8_STAGE(PG8_SA(0, 1), a2 + hstep, voffA);
;             PG8_WAIT_V(8); PG8_WAIT_L(0); PG8_BAR; PG8_MMA(0, 0, At, B0); PG8_MMA(0, 1, At, B1); PG8_BAR; PG8_SCHED;
	v_mfma_f32_16x16x32_bf16 v[54:57], v[144:147], v[180:183], v[54:57]
	v_mfma_f32_16x16x32_bf16 v[54:57], v[148:151], v[184:187], v[54:57]
	v_mfma_f32_16x16x32_bf16 v[38:41], v[144:147], v[188:191], v[38:41]
	v_mfma_f32_16x16x32_bf16 v[38:41], v[148:151], v[192:195], v[38:41]
	v_mfma_f32_16x16x32_bf16 v[22:25], v[144:147], v[202:205], v[22:25]
	v_mfma_f32_16x16x32_bf16 v[22:25], v[148:151], v[206:209], v[22:25]
	v_mfma_f32_16x16x32_bf16 v[6:9], v[144:147], v[210:213], v[6:9]
	v_mfma_f32_16x16x32_bf16 v[6:9], v[148:151], v[214:217], v[6:9]
	v_mfma_f32_16x16x32_bf16 v[50:53], v[152:155], v[180:183], v[50:53]
	v_mfma_f32_16x16x32_bf16 v[50:53], v[156:159], v[184:187], v[50:53]
	v_mfma_f32_16x16x32_bf16 v[34:37], v[152:155], v[188:191], v[34:37]
	v_mfma_f32_16x16x32_bf16 v[34:37], v[156:159], v[192:195], v[34:37]
	v_mfma_f32_16x16x32_bf16 v[18:21], v[152:155], v[202:205], v[18:21]
	v_mfma_f32_16x16x32_bf16 v[18:21], v[156:159], v[206:209], v[18:21]
	v_mfma_f32_16x16x32_bf16 v[2:5], v[152:155], v[210:213], v[2:5]
	v_mfma_f32_16x16x32_bf16 v[2:5], v[156:159], v[214:217], v[2:5]
	v_mfma_f32_16x16x32_bf16 v[62:65], v[160:163], v[180:183], v[62:65]
	v_mfma_f32_16x16x32_bf16 v[62:65], v[164:167], v[184:187], v[62:65]
	v_mfma_f32_16x16x32_bf16 v[46:49], v[160:163], v[188:191], v[46:49]
	v_mfma_f32_16x16x32_bf16 v[46:49], v[164:167], v[192:195], v[46:49]
	v_mfma_f32_16x16x32_bf16 v[30:33], v[160:163], v[202:205], v[30:33]
	v_mfma_f32_16x16x32_bf16 v[30:33], v[164:167], v[206:209], v[30:33]
	v_mfma_f32_16x16x32_bf16 v[10:13], v[160:163], v[210:213], v[10:13]
	v_mfma_f32_16x16x32_bf16 v[10:13], v[164:167], v[214:217], v[10:13]
	v_mfma_f32_16x16x32_bf16 v[58:61], v[168:171], v[180:183], v[58:61]
	v_mfma_f32_16x16x32_bf16 v[58:61], v[172:175], v[184:187], v[58:61]
	v_mfma_f32_16x16x32_bf16 v[42:45], v[168:171], v[188:191], v[42:45]
	v_mfma_f32_16x16x32_bf16 v[42:45], v[172:175], v[192:195], v[42:45]
	v_mfma_f32_16x16x32_bf16 v[26:29], v[168:171], v[202:205], v[26:29]
	v_mfma_f32_16x16x32_bf16 v[26:29], v[172:175], v[206:209], v[26:29]
	v_mfma_f32_16x16x32_bf16 v[14:17], v[168:171], v[210:213], v[14:17]
	v_mfma_f32_16x16x32_bf16 v[14:17], v[172:175], v[214:217], v[14:17]
	s_barrier
	s_setprio 0
	s_add_i32 s18, 0, 0x18000
	v_add_u32_e32 v0, s18, v176
	s_add_i32 vcc_lo, 0, 0x1c000
	ds_read_b128 v[144:147], v0
	ds_read_b128 v[148:151], v0 offset:1024
	ds_read_b128 v[152:155], v0 offset:2048
	ds_read_b128 v[156:159], v0 offset:3072
	v_add_u32_e32 v0, vcc_lo, v176
	ds_read_b128 v[160:163], v0
	ds_read_b128 v[164:167], v0 offset:1024
	ds_read_b128 v[168:171], v0 offset:2048
	ds_read_b128 v[172:175], v0 offset:3072
	s_add_u32 s38, s80, 0x40000
	s_addc_u32 s39, s81, 0
	s_mov_b32 m0, s94
	v_lshl_add_u64 v[226:227], s[38:39], 0, v[136:137]
	ds_read_b128 v[180:183], v178 offset:32768
	ds_read_b128 v[184:187], v178 offset:33792
	ds_read_b128 v[188:191], v178 offset:34816
	ds_read_b128 v[192:195], v178 offset:35840
	ds_read_b128 v[202:205], v178 offset:36864
	ds_read_b128 v[206:209], v178 offset:37888
	ds_read_b128 v[210:213], v178 offset:38912
	ds_read_b128 v[214:217], v178 offset:39936
	global_load_lds_dwordx4 v[226:227], off
	v_lshl_add_u64 v[226:227], s[38:39], 0, v[132:133]
	s_mov_b32 m0, s95
	s_nop 0
	global_load_lds_dwordx4 v[226:227], off
	s_waitcnt vmcnt(8)
	s_waitcnt lgkmcnt(0)
	s_setprio 1
	s_barrier
	v_mfma_f32_16x16x32_bf16 v[118:121], v[144:147], v[180:183], v[118:121]
	v_mfma_f32_16x16x32_bf16 v[118:121], v[148:151], v[184:187], v[118:121]
	v_mfma_f32_16x16x32_bf16 v[102:105], v[144:147], v[188:191], v[102:105]
	v_mfma_f32_16x16x32_bf16 v[102:105], v[148:151], v[192:195], v[102:105]
	v_mfma_f32_16x16x32_bf16 v[86:89], v[144:147], v[202:205], v[86:89]
	v_mfma_f32_16x16x32_bf16 v[86:89], v[148:151], v[206:209], v[86:89]
	v_mfma_f32_16x16x32_bf16 v[70:73], v[144:147], v[210:213], v[70:73]
	v_mfma_f32_16x16x32_bf16 v[70:73], v[148:151], v[214:217], v[70:73]
	v_mfma_f32_16x16x32_bf16 v[114:117], v[152:155], v[180:183], v[114:117]
	v_mfma_f32_16x16x32_bf16 v[114:117], v[156:159], v[184:187], v[114:117]
	v_mfma_f32_16x16x32_bf16 v[98:101], v[152:155], v[188:191], v[98:101]
	v_mfma_f32_16x16x32_bf16 v[98:101], v[156:159], v[192:195], v[98:101]
	v_mfma_f32_16x16x32_bf16 v[82:85], v[152:155], v[202:205], v[82:85]
	v_mfma_f32_16x16x32_bf16 v[82:85], v[156:159], v[206:209], v[82:85]
	v_mfma_f32_16x16x32_bf16 v[66:69], v[152:155], v[210:213], v[66:69]
	v_mfma_f32_16x16x32_bf16 v[66:69], v[156:159], v[214:217], v[66:69]
	v_mfma_f32_16x16x32_bf16 v[126:129], v[160:163], v[180:183], v[126:129]
	v_mfma_f32_16x16x32_bf16 v[126:129], v[164:167], v[184:187], v[126:129]
	v_mfma_f32_16x16x32_bf16 v[110:113], v[160:163], v[188:191], v[110:113]
	v_mfma_f32_16x16x32_bf16 v[110:113], v[164:167], v[192:195], v[110:113]
	v_mfma_f32_16x16x32_bf16 v[94:97], v[160:163], v[202:205], v[94:97]
	v_mfma_f32_16x16x32_bf16 v[94:97], v[164:167], v[206:209], v[94:97]
	v_mfma_f32_16x16x32_bf16 v[78:81], v[160:163], v[210:213], v[78:81]
	v_mfma_f32_16x16x32_bf16 v[78:81], v[164:167], v[214:217], v[78:81]
	v_mfma_f32_16x16x32_bf16 v[122:125], v[168:171], v[180:183], v[122:125]
	v_mfma_f32_16x16x32_bf16 v[122:125], v[172:175], v[184:187], v[122:125]
	v_mfma_f32_16x16x32_bf16 v[106:109], v[168:171], v[188:191], v[106:109]
	v_mfma_f32_16x16x32_bf16 v[106:109], v[172:175], v[192:195], v[106:109]
	v_mfma_f32_16x16x32_bf16 v[90:93], v[168:171], v[202:205], v[90:93]
	v_mfma_f32_16x16x32_bf16 v[90:93], v[172:175], v[206:209], v[90:93]
	v_mfma_f32_16x16x32_bf16 v[74:77], v[168:171], v[210:213], v[74:77]
	v_mfma_f32_16x16x32_bf16 v[74:77], v[172:175], v[214:217], v[74:77]
	s_barrier
; #define PG8_STAGE(bufoff, gbase, voff) do { _Pragma("unroll") for (int _i = 0; _i < 2; ++_i) \
;         __builtin_amdgcn_global_load_lds((const unsigned*)((const char*)(gbase) + (voff)[_i]), (PG8_LAS unsigned*)(lds + (bufoff) + ldsw + _i * 8192), 16, 0, 0); } while (0)
; #define PG8_LDA(dst, b, h) do { _Pragma("unroll") for (int m = 0; m < 4; ++m) _Pragma("unroll") for (int k = 0; k < 2; ++k) dst[m][k] = *(const PG8_LAS bf16x8*)(lds + PG8_SA(b, h) + aoff + m * 2048 + k * 1024); } while (0)
; #define PG8_MMA(ai, bj, At, Bt) do { __builtin_amdgcn_s_setprio(1); _Pragma("unroll") for (int m = 0; m < 4; ++m) _Pragma("unroll") for (int n = 0; n < 2; ++n) _Pragma("unroll") for (int k = 0; k < 2; ++k) \
;         acc[ai][bj][m][n] = __builtin_amdgcn_mfma_f32_16x16x32_bf16(Bt[n][k], At[m][k], acc[ai][bj][m][n], 0, 0, 0); __builtin_amdgcn_s_setprio(0); } while (0)
; #define PG8_WAIT_V(n) asm volatile("s_waitcnt vmcnt(" #n ")" ::: "memory")
; #define PG8_WAIT_L(n) asm volatile("s_waitcnt lgkmcnt(" #n ")" ::: "memory")
; #define PG8_BAR __builtin_amdgcn_s_barrier()
; #define PG8_SCHED __builtin_amdgcn_sched_barrier(0)
; template <class Epi, class Sched, bool ALIGN_EPI = false, bool SP2 = false>
; __device__ __forceinline__ void gemm_phase(PG8_LAS unsigned char* lds, const Gemm g, const Sched& S, const Epi& E) {
;     ...
;             PG8_LDA(At, 1, 1); PG8_STAGE(PG8_SB(1, 0), b3, voffB); PG8_STAGE(PG8_SB(1, 1), b3 + hstep, voffB); PG8_STAGE(PG8_SA(1, 0), a3, voffA);
;             PG8_WAIT_V(8); PG8_WAIT_L(0); PG8_BAR; PG8_MMA(1, 0, At, B0); PG8_MMA(1, 1, At, B1); PG8_BAR; PG8_SCHED;
;     ...
;         if constexpr (ALIGN_EPI) { if (wr == 0) PG8_BAR; }
	s_setprio 0
	s_add_i32 s18, s18, s91
	v_lshl_add_u64 v[218:219], v[218:219], 0, s[30:31]
	s_mov_b32 m0, s18
	ds_read_b128 v[180:183], v178 offset:49152
	ds_read_b128 v[184:187], v178 offset:50176
	ds_read_b128 v[188:191], v178 offset:51200
	ds_read_b128 v[192:195], v178 offset:52224
	ds_read_b128 v[202:205], v178 offset:53248
	ds_read_b128 v[206:209], v178 offset:54272
	ds_read_b128 v[210:213], v178 offset:55296
	ds_read_b128 v[214:217], v178 offset:56320
	global_load_lds_dwordx4 v[218:219], off
	s_add_i32 m0, s18, 0x2000
	s_add_u32 s38, s44, 0x40080
	v_lshl_add_u64 v[218:219], v[220:221], 0, s[30:31]
	s_addc_u32 s39, s45, 0
	s_add_i32 s18, vcc_lo, s91
	global_load_lds_dwordx4 v[218:219], off
	v_lshl_add_u64 v[218:219], s[38:39], 0, v[134:135]
	s_mov_b32 m0, s18
	s_nop 0
	global_load_lds_dwordx4 v[218:219], off
	v_lshl_add_u64 v[218:219], s[38:39], 0, v[130:131]
	s_add_i32 m0, s18, 0x2000
	s_nop 0
	global_load_lds_dwordx4 v[218:219], off
	v_lshl_add_u64 v[218:219], v[222:223], 0, s[30:31]
	s_mov_b32 m0, s7
	s_nop 0
	global_load_lds_dwordx4 v[218:219], off
	v_lshl_add_u64 v[218:219], v[224:225], 0, s[30:31]
	s_mov_b32 m0, s96
	s_nop 0
	global_load_lds_dwordx4 v[218:219], off
	s_waitcnt vmcnt(8)
	s_waitcnt lgkmcnt(0)
	s_setprio 1
	s_barrier
	v_mfma_f32_16x16x32_bf16 v[54:57], v[144:147], v[180:183], v[54:57]
	v_mfma_f32_16x16x32_bf16 v[54:57], v[148:151], v[184:187], v[54:57]
	v_mfma_f32_16x16x32_bf16 v[38:41], v[144:147], v[188:191], v[38:41]
	v_mfma_f32_16x16x32_bf16 v[38:41], v[148:151], v[192:195], v[38:41]
	v_mfma_f32_16x16x32_bf16 v[22:25], v[144:147], v[202:205], v[22:25]
	v_mfma_f32_16x16x32_bf16 v[22:25], v[148:151], v[206:209], v[22:25]
	v_mfma_f32_16x16x32_bf16 v[6:9], v[144:147], v[210:213], v[6:9]
	v_mfma_f32_16x16x32_bf16 v[6:9], v[148:151], v[214:217], v[6:9]
	v_mfma_f32_16x16x32_bf16 v[50:53], v[152:155], v[180:183], v[50:53]
	v_mfma_f32_16x16x32_bf16 v[50:53], v[156:159], v[184:187], v[50:53]
	v_mfma_f32_16x16x32_bf16 v[34:37], v[152:155], v[188:191], v[34:37]
	v_mfma_f32_16x16x32_bf16 v[34:37], v[156:159], v[192:195], v[34:37]
	v_mfma_f32_16x16x32_bf16 v[18:21], v[152:155], v[202:205], v[18:21]
	v_mfma_f32_16x16x32_bf16 v[18:21], v[156:159], v[206:209], v[18:21]
	v_mfma_f32_16x16x32_bf16 v[2:5], v[152:155], v[210:213], v[2:5]
	v_mfma_f32_16x16x32_bf16 v[2:5], v[156:159], v[214:217], v[2:5]
	v_mfma_f32_16x16x32_bf16 v[62:65], v[160:163], v[180:183], v[62:65]
	v_mfma_f32_16x16x32_bf16 v[62:65], v[164:167], v[184:187], v[62:65]
	v_mfma_f32_16x16x32_bf16 v[46:49], v[160:163], v[188:191], v[46:49]
	v_mfma_f32_16x16x32_bf16 v[46:49], v[164:167], v[192:195], v[46:49]
	v_mfma_f32_16x16x32_bf16 v[30:33], v[160:163], v[202:205], v[30:33]
	v_mfma_f32_16x16x32_bf16 v[30:33], v[164:167], v[206:209], v[30:33]
	v_mfma_f32_16x16x32_bf16 v[10:13], v[160:163], v[210:213], v[10:13]
	v_mfma_f32_16x16x32_bf16 v[10:13], v[164:167], v[214:217], v[10:13]
	v_mfma_f32_16x16x32_bf16 v[58:61], v[168:171], v[180:183], v[58:61]
	v_mfma_f32_16x16x32_bf16 v[58:61], v[172:175], v[184:187], v[58:61]
	v_mfma_f32_16x16x32_bf16 v[42:45], v[168:171], v[188:191], v[42:45]
	v_mfma_f32_16x16x32_bf16 v[42:45], v[172:175], v[192:195], v[42:45]
	v_mfma_f32_16x16x32_bf16 v[26:29], v[168:171], v[202:205], v[26:29]
	v_mfma_f32_16x16x32_bf16 v[26:29], v[172:175], v[206:209], v[26:29]
	v_mfma_f32_16x16x32_bf16 v[14:17], v[168:171], v[210:213], v[14:17]
	v_mfma_f32_16x16x32_bf16 v[14:17], v[172:175], v[214:217], v[14:17]
	s_barrier
	s_setprio 0
	s_add_i32 s85, s85, 2
	s_add_u32 s46, s46, 0x100
	s_addc_u32 s47, s47, 0
	s_add_u32 s83, s83, 0x100
	s_addc_u32 s84, s84, 0
	s_cmp_gt_u32 s85, 13
	s_cbranch_scc0 .LBB0_132
	s_and_b64 vcc, exec, s[10:11]
	s_cbranch_vccz .LBB0_135
	s_barrier

; #define PG8_STAGE(bufoff, gbase, voff) do { _Pragma("unroll") for (int _i = 0; _i < 2; ++_i) \
;         __builtin_amdgcn_global_load_lds((const unsigned*)((const char*)(gbase) + (voff)[_i]), (PG8_LAS unsigned*)(lds + (bufoff) + ldsw + _i * 8192), 16, 0, 0); } while (0)
; #define PG8_LDA(dst, b, h) do { _Pragma("unroll") for (int m = 0; m < 4; ++m) _Pragma("unroll") for (int k = 0; k < 2; ++k) dst[m][k] = *(const PG8_LAS bf16x8*)(lds + PG8_SA(b, h) + aoff + m * 2048 + k * 1024); } while (0)
; #define PG8_LDB(dst, b, h) do { _Pragma("unroll") for (int n = 0; n < 2; ++n) _Pragma("unroll") for (int k = 0; k < 2; ++k) dst[n][k] = *(const PG8_LAS bf16x8*)(lds + PG8_SB(b, h) + boff + n * 2048 + k * 1024); } while (0)
; #define PG8_MMA(ai, bj, At, Bt) do { __builtin_amdgcn_s_setprio(1); _Pragma("unroll") for (int m = 0; m < 4; ++m) _Pragma("unroll") for (int n = 0; n < 2; ++n) _Pragma("unroll") for (int k = 0; k < 2; ++k) \
;         acc[ai][bj][m][n] = __builtin_amdgcn_mfma_f32_16x16x32_bf16(Bt[n][k], At[m][k], acc[ai][bj][m][n], 0, 0, 0); __builtin_amdgcn_s_setprio(0); } while (0)
; #define PG8_WAIT_V(n) asm volatile("s_waitcnt vmcnt(" #n ")" ::: "memory")
; #define PG8_WAIT_L(n) asm volatile("s_waitcnt lgkmcnt(" #n ")" ::: "memory")
; template <class Epi, class Sched, bool ALIGN_EPI = false, bool SP2 = false>
; __device__ __forceinline__ void gemm_phase(PG8_LAS unsigned char* lds, const Gemm g, const Sched& S, const Epi& E) {
;     ...
;             const bool last = (t == nt - 2);
;             const char* a1 = cA + (size_t)(t + 1) * kstep;
;             const char* a2 = last ? nA : cA + (size_t)(t + 2) * kstep; const char* b2 = last ? nB : cB + (size_t)(t + 2) * kstep;
;             const char* a3 = a2 + kstep; const char* b3 = b2 + kstep;
;             if (last && has_next) S.a_ready(nxt);
;             if constexpr (SP2) {
;             PG8_LDB(B0, 0, 0); PG8_LDB(B1, 0, 1); PG8_SCHED; PG8_LDA(At, 0, 0); PG8_STAGE(PG8_SA(1, 1), a1 + hstep, voffA);
;             PG8_WAIT_V(8); PG8_WAIT_L(0); PG8_BAR; PG8_MMA(0, 0, At, B0); PG8_MMA(0, 1, At, B1); PG8_BAR; PG8_SCHED;
;             PG8_LDA(At, 0, 1); PG8_STAGE(PG8_SB(0, 0), b2, voffB); PG8_STAGE(PG8_SB(0, 1), b2 + hstep, voffB); PG8_STAGE(PG8_SA(0, 0), a2, voffA);
;             PG8_WAIT_V(8); PG8_WAIT_L(0); PG8_BAR; PG8_MMA(1, 0, At, B0); PG8_MMA(1, 1, At, B1); PG8_BAR; PG8_SCHED;
.LBB0_220:
	s_add_u32 s18, s60, 0xfffc0080
	s_addc_u32 s38, s61, -1
	s_add_i32 s39, 0, 0x10000
	s_cmp_eq_u32 s82, 12
	s_cselect_b32 s65, s47, s38
	s_cselect_b32 s64, s78, s18
	v_add_u32_e32 v145, s39, v141
	s_cselect_b32 s57, s49, s81
	s_cselect_b32 s56, s79, s80
	s_add_i32 s18, 0, 0x14000
	ds_read_b128 v[146:149], v145
	ds_read_b128 v[150:153], v145 offset:1024
	ds_read_b128 v[154:157], v145 offset:2048
	ds_read_b128 v[158:161], v145 offset:3072
	v_add_u32_e32 v145, s18, v141
	ds_read_b128 v[162:165], v145
	ds_read_b128 v[166:169], v145 offset:1024
	ds_read_b128 v[170:173], v145 offset:2048
	ds_read_b128 v[174:177], v145 offset:3072
	v_lshl_add_u64 v[194:195], s[60:61], 0, v[136:137]
	s_add_i32 m0, s29, 0xc000
	ds_read_b128 v[178:181], v144
	ds_read_b128 v[182:185], v144 offset:1024
	ds_read_b128 v[186:189], v144 offset:2048
	ds_read_b128 v[190:193], v144 offset:3072
	ds_read_b128 v[202:205], v144 offset:4096
	ds_read_b128 v[206:209], v144 offset:5120
	ds_read_b128 v[210:213], v144 offset:6144
	ds_read_b128 v[214:217], v144 offset:7168
	global_load_lds_dwordx4 v[194:195], off
	v_lshl_add_u64 v[194:195], s[60:61], 0, v[138:139]
	s_add_i32 m0, s29, 0xe000
	s_nop 0
	global_load_lds_dwordx4 v[194:195], off
	s_waitcnt vmcnt(8)
	s_waitcnt lgkmcnt(0)
	s_setprio 1
	s_barrier
	v_mfma_f32_16x16x32_bf16 v[114:117], v[146:149], v[178:181], v[114:117]
	v_mfma_f32_16x16x32_bf16 v[114:117], v[150:153], v[182:185], v[114:117]
	v_mfma_f32_16x16x32_bf16 v[98:101], v[146:149], v[186:189], v[98:101]
	v_mfma_f32_16x16x32_bf16 v[98:101], v[150:153], v[190:193], v[98:101]
	v_mfma_f32_16x16x32_bf16 v[82:85], v[146:149], v[202:205], v[82:85]
	v_mfma_f32_16x16x32_bf16 v[82:85], v[150:153], v[206:209], v[82:85]
	v_mfma_f32_16x16x32_bf16 v[66:69], v[146:149], v[210:213], v[66:69]
	v_mfma_f32_16x16x32_bf16 v[66:69], v[150:153], v[214:217], v[66:69]
	v_mfma_f32_16x16x32_bf16 v[118:121], v[154:157], v[178:181], v[118:121]
	v_mfma_f32_16x16x32_bf16 v[118:121], v[158:161], v[182:185], v[118:121]
	v_mfma_f32_16x16x32_bf16 v[102:105], v[154:157], v[186:189], v[102:105]
	v_mfma_f32_16x16x32_bf16 v[102:105], v[158:161], v[190:193], v[102:105]
	v_mfma_f32_16x16x32_bf16 v[86:89], v[154:157], v[202:205], v[86:89]
	v_mfma_f32_16x16x32_bf16 v[86:89], v[158:161], v[206:209], v[86:89]
	v_mfma_f32_16x16x32_bf16 v[70:73], v[154:157], v[210:213], v[70:73]
	v_mfma_f32_16x16x32_bf16 v[70:73], v[158:161], v[214:217], v[70:73]
	v_mfma_f32_16x16x32_bf16 v[122:125], v[162:165], v[178:181], v[122:125]
	v_mfma_f32_16x16x32_bf16 v[122:125], v[166:169], v[182:185], v[122:125]
	v_mfma_f32_16x16x32_bf16 v[106:109], v[162:165], v[186:189], v[106:109]
	v_mfma_f32_16x16x32_bf16 v[106:109], v[166:169], v[190:193], v[106:109]
	v_mfma_f32_16x16x32_bf16 v[90:93], v[162:165], v[202:205], v[90:93]
	v_mfma_f32_16x16x32_bf16 v[90:93], v[166:169], v[206:209], v[90:93]
	v_mfma_f32_16x16x32_bf16 v[74:77], v[162:165], v[210:213], v[74:77]
	v_mfma_f32_16x16x32_bf16 v[74:77], v[166:169], v[214:217], v[74:77]
	v_mfma_f32_16x16x32_bf16 v[126:129], v[170:173], v[178:181], v[126:129]
	v_mfma_f32_16x16x32_bf16 v[126:129], v[174:177], v[182:185], v[126:129]
	v_mfma_f32_16x16x32_bf16 v[110:113], v[170:173], v[186:189], v[110:113]
	v_mfma_f32_16x16x32_bf16 v[110:113], v[174:177], v[190:193], v[110:113]
	v_mfma_f32_16x16x32_bf16 v[94:97], v[170:173], v[202:205], v[94:97]
	v_mfma_f32_16x16x32_bf16 v[94:97], v[174:177], v[206:209], v[94:97]
	v_mfma_f32_16x16x32_bf16 v[78:81], v[170:173], v[210:213], v[78:81]
	v_mfma_f32_16x16x32_bf16 v[78:81], v[174:177], v[214:217], v[78:81]
	s_barrier
	s_setprio 0
	s_add_i32 s38, s39, s27
	v_lshl_add_u64 v[194:195], s[56:57], 0, v[0:1]
	s_mov_b32 m0, s38
	ds_read_b128 v[178:181], v144 offset:16384
	ds_read_b128 v[182:185], v144 offset:17408
	ds_read_b128 v[186:189], v144 offset:18432
	ds_read_b128 v[190:193], v144 offset:19456
	ds_read_b128 v[202:205], v144 offset:20480
	ds_read_b128 v[206:209], v144 offset:21504
	ds_read_b128 v[210:213], v144 offset:22528
	ds_read_b128 v[214:217], v144 offset:23552
	global_load_lds_dwordx4 v[194:195], off
	s_add_i32 m0, s38, 0x2000
	s_add_u32 s38, s56, 0x40000
	v_lshl_add_u64 v[218:219], s[56:57], 0, v[130:131]
	s_addc_u32 s39, s57, 0
	s_add_i32 s18, s18, s27
	global_load_lds_dwordx4 v[218:219], off
	v_lshl_add_u64 v[220:221], s[38:39], 0, v[0:1]
	s_mov_b32 m0, s18
	v_lshl_add_u64 v[222:223], s[64:65], 0, v[132:133]
	global_load_lds_dwordx4 v[220:221], off
	v_lshl_add_u64 v[220:221], s[38:39], 0, v[130:131]
	s_add_i32 m0, s18, 0x2000
	s_nop 0
	global_load_lds_dwordx4 v[220:221], off
	v_lshl_add_u64 v[220:221], s[64:65], 0, v[134:135]
	s_mov_b32 m0, s29
	s_nop 0
	global_load_lds_dwordx4 v[220:221], off
	s_mov_b32 m0, s33
	s_nop 0
	global_load_lds_dwordx4 v[222:223], off
	s_waitcnt vmcnt(8)
	s_waitcnt lgkmcnt(0)
	s_setprio 1
	s_barrier
; #define PG8_STAGE(bufoff, gbase, voff) do { _Pragma("unroll") for (int _i = 0; _i < 2; ++_i) \
;         __builtin_amdgcn_global_load_lds((const unsigned*)((const char*)(gbase) + (voff)[_i]), (PG8_LAS unsigned*)(lds + (bufoff) + ldsw + _i * 8192), 16, 0, 0); } while (0)
; #define PG8_LDA(dst, b, h) do { _Pragma("unroll") for (int m = 0; m < 4; ++m) _Pragma("unroll") for (int k = 0; k < 2; ++k) dst[m][k] = *(const PG8_LAS bf16x8*)(lds + PG8_SA(b, h) + aoff + m * 2048 + k * 1024); } while (0)
; #define PG8_LDB(dst, b, h) do { _Pragma("unroll") for (int n = 0; n < 2; ++n) _Pragma("unroll") for (int k = 0; k < 2; ++k) dst[n][k] = *(const PG8_LAS bf16x8*)(lds + PG8_SB(b, h) + boff + n * 2048 + k * 1024); } while (0)
; #define PG8_MMA(ai, bj, At, Bt) do { __builtin_amdgcn_s_setprio(1); _Pragma("unroll") for (int m = 0; m < 4; ++m) _Pragma("unroll") for (int n = 0; n < 2; ++n) _Pragma("unroll") for (int k = 0; k < 2; ++k) \
;         acc[ai][bj][m][n] = __builtin_amdgcn_mfma_f32_16x16x32_bf16(Bt[n][k], At[m][k], acc[ai][bj][m][n], 0, 0, 0); __builtin_amdgcn_s_setprio(0); } while (0)
; #define PG8_WAIT_V(n) asm volatile("s_waitcnt vmcnt(" #n ")" ::: "memory")
; #define PG8_WAIT_L(n) asm volatile("s_waitcnt lgkmcnt(" #n ")" ::: "memory")
; #define PG8_BAR __builtin_amdgcn_s_barrier()
; #define PG8_SCHED __builtin_amdgcn_sched_barrier(0)
; template <class Epi, class Sched, bool ALIGN_EPI = false, bool SP2 = false>
; __device__ __forceinline__ void gemm_phase(PG8_LAS unsigned char* lds, const Gemm g, const Sched& S, const Epi& E) {
;     ...
;             PG8_WAIT_V(8); PG8_WAIT_L(0); PG8_BAR; PG8_MMA(1, 0, At, B0); PG8_MMA(1, 1, At, B1); PG8_BAR; PG8_SCHED;
;             PG8_LDB(B0, 1, 0); PG8_LDB(B1, 1, 1); PG8_SCHED; PG8_LDA(At, 1, 0); PG8_STAGE(PG8_SA(0, 1), a2 + hstep, voffA);
;             PG8_WAIT_V(8); PG8_WAIT_L(0); PG8_BAR; PG8_MMA(0, 0, At, B0); PG8_MMA(0, 1, At, B1); PG8_BAR; PG8_SCHED;
	v_mfma_f32_16x16x32_bf16 v[50:53], v[146:149], v[178:181], v[50:53]
	v_mfma_f32_16x16x32_bf16 v[50:53], v[150:153], v[182:185], v[50:53]
	v_mfma_f32_16x16x32_bf16 v[34:37], v[146:149], v[186:189], v[34:37]
	v_mfma_f32_16x16x32_bf16 v[34:37], v[150:153], v[190:193], v[34:37]
	v_mfma_f32_16x16x32_bf16 v[18:21], v[146:149], v[202:205], v[18:21]
	v_mfma_f32_16x16x32_bf16 v[18:21], v[150:153], v[206:209], v[18:21]
	v_mfma_f32_16x16x32_bf16 v[2:5], v[146:149], v[210:213], v[2:5]
	v_mfma_f32_16x16x32_bf16 v[2:5], v[150:153], v[214:217], v[2:5]
	v_mfma_f32_16x16x32_bf16 v[54:57], v[154:157], v[178:181], v[54:57]
	v_mfma_f32_16x16x32_bf16 v[54:57], v[158:161], v[182:185], v[54:57]
	v_mfma_f32_16x16x32_bf16 v[38:41], v[154:157], v[186:189], v[38:41]
	v_mfma_f32_16x16x32_bf16 v[38:41], v[158:161], v[190:193], v[38:41]
	v_mfma_f32_16x16x32_bf16 v[22:25], v[154:157], v[202:205], v[22:25]
	v_mfma_f32_16x16x32_bf16 v[22:25], v[158:161], v[206:209], v[22:25]
	v_mfma_f32_16x16x32_bf16 v[6:9], v[154:157], v[210:213], v[6:9]
	v_mfma_f32_16x16x32_bf16 v[6:9], v[158:161], v[214:217], v[6:9]
	v_mfma_f32_16x16x32_bf16 v[58:61], v[162:165], v[178:181], v[58:61]
	v_mfma_f32_16x16x32_bf16 v[58:61], v[166:169], v[182:185], v[58:61]
	v_mfma_f32_16x16x32_bf16 v[42:45], v[162:165], v[186:189], v[42:45]
	v_mfma_f32_16x16x32_bf16 v[42:45], v[166:169], v[190:193], v[42:45]
	v_mfma_f32_16x16x32_bf16 v[26:29], v[162:165], v[202:205], v[26:29]
	v_mfma_f32_16x16x32_bf16 v[26:29], v[166:169], v[206:209], v[26:29]
	v_mfma_f32_16x16x32_bf16 v[10:13], v[162:165], v[210:213], v[10:13]
	v_mfma_f32_16x16x32_bf16 v[10:13], v[166:169], v[214:217], v[10:13]
	v_mfma_f32_16x16x32_bf16 v[62:65], v[170:173], v[178:181], v[62:65]
	v_mfma_f32_16x16x32_bf16 v[62:65], v[174:177], v[182:185], v[62:65]
	v_mfma_f32_16x16x32_bf16 v[46:49], v[170:173], v[186:189], v[46:49]
	v_mfma_f32_16x16x32_bf16 v[46:49], v[174:177], v[190:193], v[46:49]
	v_mfma_f32_16x16x32_bf16 v[30:33], v[170:173], v[202:205], v[30:33]
	v_mfma_f32_16x16x32_bf16 v[30:33], v[174:177], v[206:209], v[30:33]
	v_mfma_f32_16x16x32_bf16 v[14:17], v[170:173], v[210:213], v[14:17]
	v_mfma_f32_16x16x32_bf16 v[14:17], v[174:177], v[214:217], v[14:17]
	s_barrier
	s_setprio 0
	s_add_i32 s18, 0, 0x18000
	v_add_u32_e32 v145, s18, v141
	s_add_i32 s83, 0, 0x1c000
	ds_read_b128 v[146:149], v145
	ds_read_b128 v[150:153], v145 offset:1024
	ds_read_b128 v[154:157], v145 offset:2048
	ds_read_b128 v[158:161], v145 offset:3072
	v_add_u32_e32 v145, s83, v141
	ds_read_b128 v[162:165], v145
	ds_read_b128 v[166:169], v145 offset:1024
	ds_read_b128 v[170:173], v145 offset:2048
	ds_read_b128 v[174:177], v145 offset:3072
	s_add_u32 s38, s64, 0x40000
	s_addc_u32 s39, s65, 0
	s_mov_b32 m0, s58
	v_lshl_add_u64 v[224:225], s[38:39], 0, v[134:135]
	ds_read_b128 v[178:181], v144 offset:32768
	ds_read_b128 v[182:185], v144 offset:33792
	ds_read_b128 v[186:189], v144 offset:34816
	ds_read_b128 v[190:193], v144 offset:35840
	ds_read_b128 v[202:205], v144 offset:36864
	ds_read_b128 v[206:209], v144 offset:37888
	ds_read_b128 v[210:213], v144 offset:38912
	ds_read_b128 v[214:217], v144 offset:39936
	global_load_lds_dwordx4 v[224:225], off
	v_lshl_add_u64 v[224:225], s[38:39], 0, v[132:133]
	s_mov_b32 m0, s69
	s_nop 0
	global_load_lds_dwordx4 v[224:225], off
	s_waitcnt vmcnt(8)
	s_waitcnt lgkmcnt(0)
	s_setprio 1
	s_barrier
	v_mfma_f32_16x16x32_bf16 v[114:117], v[146:149], v[178:181], v[114:117]
	v_mfma_f32_16x16x32_bf16 v[114:117], v[150:153], v[182:185], v[114:117]
	v_mfma_f32_16x16x32_bf16 v[98:101], v[146:149], v[186:189], v[98:101]
	v_mfma_f32_16x16x32_bf16 v[98:101], v[150:153], v[190:193], v[98:101]
	v_mfma_f32_16x16x32_bf16 v[82:85], v[146:149], v[202:205], v[82:85]
	v_mfma_f32_16x16x32_bf16 v[82:85], v[150:153], v[206:209], v[82:85]
	v_mfma_f32_16x16x32_bf16 v[66:69], v[146:149], v[210:213], v[66:69]
	v_mfma_f32_16x16x32_bf16 v[66:69], v[150:153], v[214:217], v[66:69]
	v_mfma_f32_16x16x32_bf16 v[118:121], v[154:157], v[178:181], v[118:121]
	v_mfma_f32_16x16x32_bf16 v[118:121], v[158:161], v[182:185], v[118:121]
	v_mfma_f32_16x16x32_bf16 v[102:105], v[154:157], v[186:189], v[102:105]
	v_mfma_f32_16x16x32_bf16 v[102:105], v[158:161], v[190:193], v[102:105]
	v_mfma_f32_16x16x32_bf16 v[86:89], v[154:157], v[202:205], v[86:89]
	v_mfma_f32_16x16x32_bf16 v[86:89], v[158:161], v[206:209], v[86:89]
	v_mfma_f32_16x16x32_bf16 v[70:73], v[154:157], v[210:213], v[70:73]
	v_mfma_f32_16x16x32_bf16 v[70:73], v[158:161], v[214:217], v[70:73]
	v_mfma_f32_16x16x32_bf16 v[122:125], v[162:165], v[178:181], v[122:125]
	v_mfma_f32_16x16x32_bf16 v[122:125], v[166:169], v[182:185], v[122:125]
	v_mfma_f32_16x16x32_bf16 v[106:109], v[162:165], v[186:189], v[106:109]
	v_mfma_f32_16x16x32_bf16 v[106:109], v[166:169], v[190:193], v[106:109]
	v_mfma_f32_16x16x32_bf16 v[90:93], v[162:165], v[202:205], v[90:93]
	v_mfma_f32_16x16x32_bf16 v[90:93], v[166:169], v[206:209], v[90:93]
	v_mfma_f32_16x16x32_bf16 v[74:77], v[162:165], v[210:213], v[74:77]
	v_mfma_f32_16x16x32_bf16 v[74:77], v[166:169], v[214:217], v[74:77]
	v_mfma_f32_16x16x32_bf16 v[126:129], v[170:173], v[178:181], v[126:129]
	v_mfma_f32_16x16x32_bf16 v[126:129], v[174:177], v[182:185], v[126:129]
	v_mfma_f32_16x16x32_bf16 v[110:113], v[170:173], v[186:189], v[110:113]
	v_mfma_f32_16x16x32_bf16 v[110:113], v[174:177], v[190:193], v[110:113]
	v_mfma_f32_16x16x32_bf16 v[94:97], v[170:173], v[202:205], v[94:97]
	v_mfma_f32_16x16x32_bf16 v[94:97], v[174:177], v[206:209], v[94:97]
	v_mfma_f32_16x16x32_bf16 v[78:81], v[170:173], v[210:213], v[78:81]
	v_mfma_f32_16x16x32_bf16 v[78:81], v[174:177], v[214:217], v[78:81]
	s_barrier
; #define PG8_STAGE(bufoff, gbase, voff) do { _Pragma("unroll") for (int _i = 0; _i < 2; ++_i) \
;         __builtin_amdgcn_global_load_lds((const unsigned*)((const char*)(gbase) + (voff)[_i]), (PG8_LAS unsigned*)(lds + (bufoff) + ldsw + _i * 8192), 16, 0, 0); } while (0)
; #define PG8_LDA(dst, b, h) do { _Pragma("unroll") for (int m = 0; m < 4; ++m) _Pragma("unroll") for (int k = 0; k < 2; ++k) dst[m][k] = *(const PG8_LAS bf16x8*)(lds + PG8_SA(b, h) + aoff + m * 2048 + k * 1024); } while (0)
; #define PG8_MMA(ai, bj, At, Bt) do { __builtin_amdgcn_s_setprio(1); _Pragma("unroll") for (int m = 0; m < 4; ++m) _Pragma("unroll") for (int n = 0; n < 2; ++n) _Pragma("unroll") for (int k = 0; k < 2; ++k) \
;         acc[ai][bj][m][n] = __builtin_amdgcn_mfma_f32_16x16x32_bf16(Bt[n][k], At[m][k], acc[ai][bj][m][n], 0, 0, 0); __builtin_amdgcn_s_setprio(0); } while (0)
; #define PG8_WAIT_V(n) asm volatile("s_waitcnt vmcnt(" #n ")" ::: "memory")
; #define PG8_WAIT_L(n) asm volatile("s_waitcnt lgkmcnt(" #n ")" ::: "memory")
; #define PG8_BAR __builtin_amdgcn_s_barrier()
; #define PG8_SCHED __builtin_amdgcn_sched_barrier(0)
; template <class Epi, class Sched, bool ALIGN_EPI = false, bool SP2 = false>
; __device__ __forceinline__ void gemm_phase(PG8_LAS unsigned char* lds, const Gemm g, const Sched& S, const Epi& E) {
;     ...
;             PG8_LDA(At, 1, 1); PG8_STAGE(PG8_SB(1, 0), b3, voffB); PG8_STAGE(PG8_SB(1, 1), b3 + hstep, voffB); PG8_STAGE(PG8_SA(1, 0), a3, voffA);
;             PG8_WAIT_V(8); PG8_WAIT_L(0); PG8_BAR; PG8_MMA(1, 0, At, B0); PG8_MMA(1, 1, At, B1); PG8_BAR; PG8_SCHED;
;     ...
;         if constexpr (ALIGN_EPI) { if (wr == 0) PG8_BAR; }
	s_setprio 0
	s_add_i32 s18, s18, s27
	v_lshl_add_u64 v[194:195], v[194:195], 0, s[30:31]
	s_mov_b32 m0, s18
	ds_read_b128 v[178:181], v144 offset:49152
	ds_read_b128 v[182:185], v144 offset:50176
	ds_read_b128 v[186:189], v144 offset:51200
	ds_read_b128 v[190:193], v144 offset:52224
	ds_read_b128 v[202:205], v144 offset:53248
	ds_read_b128 v[206:209], v144 offset:54272
	ds_read_b128 v[210:213], v144 offset:55296
	ds_read_b128 v[214:217], v144 offset:56320
	global_load_lds_dwordx4 v[194:195], off
	s_add_i32 m0, s18, 0x2000
	s_add_u32 s38, s56, 0x40080
	v_lshl_add_u64 v[194:195], v[218:219], 0, s[30:31]
	s_addc_u32 s39, s57, 0
	s_add_i32 s18, s83, s27
	global_load_lds_dwordx4 v[194:195], off
	v_lshl_add_u64 v[194:195], s[38:39], 0, v[0:1]
	s_mov_b32 m0, s18
	s_nop 0
	global_load_lds_dwordx4 v[194:195], off
	v_lshl_add_u64 v[194:195], s[38:39], 0, v[130:131]
	s_add_i32 m0, s18, 0x2000
	s_nop 0
	global_load_lds_dwordx4 v[194:195], off
	v_lshl_add_u64 v[194:195], v[220:221], 0, s[30:31]
	s_mov_b32 m0, s71
	s_nop 0
	global_load_lds_dwordx4 v[194:195], off
	v_lshl_add_u64 v[194:195], v[222:223], 0, s[30:31]
	s_mov_b32 m0, s72
	s_nop 0
	global_load_lds_dwordx4 v[194:195], off
	s_waitcnt vmcnt(8)
	s_waitcnt lgkmcnt(0)
	s_setprio 1
	s_barrier
	v_mfma_f32_16x16x32_bf16 v[50:53], v[146:149], v[178:181], v[50:53]
	v_mfma_f32_16x16x32_bf16 v[50:53], v[150:153], v[182:185], v[50:53]
	v_mfma_f32_16x16x32_bf16 v[34:37], v[146:149], v[186:189], v[34:37]
	v_mfma_f32_16x16x32_bf16 v[34:37], v[150:153], v[190:193], v[34:37]
	v_mfma_f32_16x16x32_bf16 v[18:21], v[146:149], v[202:205], v[18:21]
	v_mfma_f32_16x16x32_bf16 v[18:21], v[150:153], v[206:209], v[18:21]
	v_mfma_f32_16x16x32_bf16 v[2:5], v[146:149], v[210:213], v[2:5]
	v_mfma_f32_16x16x32_bf16 v[2:5], v[150:153], v[214:217], v[2:5]
	v_mfma_f32_16x16x32_bf16 v[54:57], v[154:157], v[178:181], v[54:57]
	v_mfma_f32_16x16x32_bf16 v[54:57], v[158:161], v[182:185], v[54:57]
	v_mfma_f32_16x16x32_bf16 v[38:41], v[154:157], v[186:189], v[38:41]
	v_mfma_f32_16x16x32_bf16 v[38:41], v[158:161], v[190:193], v[38:41]
	v_mfma_f32_16x16x32_bf16 v[22:25], v[154:157], v[202:205], v[22:25]
	v_mfma_f32_16x16x32_bf16 v[22:25], v[158:161], v[206:209], v[22:25]
	v_mfma_f32_16x16x32_bf16 v[6:9], v[154:157], v[210:213], v[6:9]
	v_mfma_f32_16x16x32_bf16 v[6:9], v[158:161], v[214:217], v[6:9]
	v_mfma_f32_16x16x32_bf16 v[58:61], v[162:165], v[178:181], v[58:61]
	v_mfma_f32_16x16x32_bf16 v[58:61], v[166:169], v[182:185], v[58:61]
	v_mfma_f32_16x16x32_bf16 v[42:45], v[162:165], v[186:189], v[42:45]
	v_mfma_f32_16x16x32_bf16 v[42:45], v[166:169], v[190:193], v[42:45]
	v_mfma_f32_16x16x32_bf16 v[26:29], v[162:165], v[202:205], v[26:29]
	v_mfma_f32_16x16x32_bf16 v[26:29], v[166:169], v[206:209], v[26:29]
	v_mfma_f32_16x16x32_bf16 v[10:13], v[162:165], v[210:213], v[10:13]
	v_mfma_f32_16x16x32_bf16 v[10:13], v[166:169], v[214:217], v[10:13]
	v_mfma_f32_16x16x32_bf16 v[62:65], v[170:173], v[178:181], v[62:65]
	v_mfma_f32_16x16x32_bf16 v[62:65], v[174:177], v[182:185], v[62:65]
	v_mfma_f32_16x16x32_bf16 v[46:49], v[170:173], v[186:189], v[46:49]
	v_mfma_f32_16x16x32_bf16 v[46:49], v[174:177], v[190:193], v[46:49]
	v_mfma_f32_16x16x32_bf16 v[30:33], v[170:173], v[202:205], v[30:33]
	v_mfma_f32_16x16x32_bf16 v[30:33], v[174:177], v[206:209], v[30:33]
	v_mfma_f32_16x16x32_bf16 v[14:17], v[170:173], v[210:213], v[14:17]
	v_mfma_f32_16x16x32_bf16 v[14:17], v[174:177], v[214:217], v[14:17]
	s_barrier
	s_setprio 0
	s_add_i32 s82, s82, 2
	s_add_u32 s60, s60, 0x100
	s_addc_u32 s61, s61, 0
	s_add_u32 s80, s80, 0x100
	s_addc_u32 s81, s81, 0
	s_cmp_gt_u32 s82, 13
	s_cbranch_scc0 .LBB0_220
	s_and_b64 vcc, exec, s[44:45]
	s_cbranch_vccz .LBB0_223
	s_barrier

; #define PG8_STAGE(bufoff, gbase, voff) do { _Pragma("unroll") for (int _i = 0; _i < 2; ++_i) \
;         __builtin_amdgcn_global_load_lds((const unsigned*)((const char*)(gbase) + (voff)[_i]), (PG8_LAS unsigned*)(lds + (bufoff) + ldsw + _i * 8192), 16, 0, 0); } while (0)
; #define PG8_LDA(dst, b, h) do { _Pragma("unroll") for (int m = 0; m < 4; ++m) _Pragma("unroll") for (int k = 0; k < 2; ++k) dst[m][k] = *(const PG8_LAS bf16x8*)(lds + PG8_SA(b, h) + aoff + m * 2048 + k * 1024); } while (0)
; #define PG8_LDB(dst, b, h) do { _Pragma("unroll") for (int n = 0; n < 2; ++n) _Pragma("unroll") for (int k = 0; k < 2; ++k) dst[n][k] = *(const PG8_LAS bf16x8*)(lds + PG8_SB(b, h) + boff + n * 2048 + k * 1024); } while (0)
; #define PG8_MMA(ai, bj, At, Bt) do { __builtin_amdgcn_s_setprio(1); _Pragma("unroll") for (int m = 0; m < 4; ++m) _Pragma("unroll") for (int n = 0; n < 2; ++n) _Pragma("unroll") for (int k = 0; k < 2; ++k) \
;         acc[ai][bj][m][n] = __builtin_amdgcn_mfma_f32_16x16x32_bf16(Bt[n][k], At[m][k], acc[ai][bj][m][n], 0, 0, 0); __builtin_amdgcn_s_setprio(0); } while (0)
; #define PG8_WAIT_V(n) asm volatile("s_waitcnt vmcnt(" #n ")" ::: "memory")
; #define PG8_WAIT_L(n) asm volatile("s_waitcnt lgkmcnt(" #n ")" ::: "memory")
; template <class Epi, class Sched, bool ALIGN_EPI = false, bool SP2 = false>
; __device__ __forceinline__ void gemm_phase(PG8_LAS unsigned char* lds, const Gemm g, const Sched& S, const Epi& E) {
;     ...
;             const bool last = (t == nt - 2);
;             const char* a1 = cA + (size_t)(t + 1) * kstep;
;             const char* a2 = last ? nA : cA + (size_t)(t + 2) * kstep; const char* b2 = last ? nB : cB + (size_t)(t + 2) * kstep;
;             const char* a3 = a2 + kstep; const char* b3 = b2 + kstep;
;             if (last && has_next) S.a_ready(nxt);
;             if constexpr (SP2) {
;             PG8_LDB(B0, 0, 0); PG8_LDB(B1, 0, 1); PG8_SCHED; PG8_LDA(At, 0, 0); PG8_STAGE(PG8_SA(1, 1), a1 + hstep, voffA);
;             PG8_WAIT_V(8); PG8_WAIT_L(0); PG8_BAR; PG8_MMA(0, 0, At, B0); PG8_MMA(0, 1, At, B1); PG8_BAR; PG8_SCHED;
;             PG8_LDA(At, 0, 1); PG8_STAGE(PG8_SB(0, 0), b2, voffB); PG8_STAGE(PG8_SB(0, 1), b2 + hstep, voffB); PG8_STAGE(PG8_SA(0, 0), a2, voffA);
;             PG8_WAIT_V(8); PG8_WAIT_L(0); PG8_BAR; PG8_MMA(1, 0, At, B0); PG8_MMA(1, 1, At, B1); PG8_BAR; PG8_SCHED;
.LBB0_274:
	s_add_i32 vcc_lo, s46, 2
	s_add_u32 s38, s48, 0x80
	s_addc_u32 s39, s49, 0
	s_add_i32 vcc_hi, 0, 0x10000
	s_cmp_eq_u32 s99, s46
	s_cselect_b32 s47, s81, s39
	s_cselect_b32 s46, s80, s38
	s_cselect_b32 s39, s83, s51
	s_cselect_b32 s38, s82, s50
	s_add_i32 s18, 0, 0x14000
	v_add_u32_e32 v142, vcc_hi, v245
	v_add_u32_e32 v158, s18, v245
	ds_read_b128 v[110:113], v142
	ds_read_b128 v[118:121], v142 offset:1024
	ds_read_b128 v[138:141], v142 offset:2048
	ds_read_b128 v[142:145], v142 offset:3072
	ds_read_b128 v[146:149], v158
	ds_read_b128 v[150:153], v158 offset:1024
	ds_read_b128 v[154:157], v158 offset:2048
	ds_read_b128 v[158:161], v158 offset:3072
	v_lshl_add_u64 v[210:211], s[48:49], 0, v[206:207]
	s_add_i32 m0, s92, 0xc000
	ds_read_b128 v[162:165], v247
	ds_read_b128 v[166:169], v247 offset:1024
	ds_read_b128 v[170:173], v247 offset:2048
	ds_read_b128 v[174:177], v247 offset:3072
	ds_read_b128 v[178:181], v247 offset:4096
	ds_read_b128 v[182:185], v247 offset:5120
	ds_read_b128 v[186:189], v247 offset:6144
	ds_read_b128 v[190:193], v247 offset:7168
	global_load_lds_dwordx4 v[210:211], off
	v_lshl_add_u64 v[210:211], s[48:49], 0, v[208:209]
	s_add_i32 m0, s92, 0xe000
	s_nop 0
	global_load_lds_dwordx4 v[210:211], off
	s_waitcnt vmcnt(8)
	s_waitcnt lgkmcnt(0)
	s_setprio 1
	s_barrier
	v_mfma_f32_16x16x32_bf16 v[130:133], v[110:113], v[162:165], v[130:133]
	v_mfma_f32_16x16x32_bf16 v[130:133], v[118:121], v[166:169], v[130:133]
	v_mfma_f32_16x16x32_bf16 v[114:117], v[110:113], v[170:173], v[114:117]
	v_mfma_f32_16x16x32_bf16 v[114:117], v[118:121], v[174:177], v[114:117]
	v_mfma_f32_16x16x32_bf16 v[94:97], v[110:113], v[178:181], v[94:97]
	v_mfma_f32_16x16x32_bf16 v[94:97], v[118:121], v[182:185], v[94:97]
	v_mfma_f32_16x16x32_bf16 v[78:81], v[110:113], v[186:189], v[78:81]
	v_mfma_f32_16x16x32_bf16 v[78:81], v[118:121], v[190:193], v[78:81]
	v_mfma_f32_16x16x32_bf16 v[134:137], v[138:141], v[162:165], v[134:137]
	v_mfma_f32_16x16x32_bf16 v[134:137], v[142:145], v[166:169], v[134:137]
	v_mfma_f32_16x16x32_bf16 v[106:109], v[138:141], v[170:173], v[106:109]
	v_mfma_f32_16x16x32_bf16 v[106:109], v[142:145], v[174:177], v[106:109]
	v_mfma_f32_16x16x32_bf16 v[90:93], v[138:141], v[178:181], v[90:93]
	v_mfma_f32_16x16x32_bf16 v[90:93], v[142:145], v[182:185], v[90:93]
	v_mfma_f32_16x16x32_bf16 v[74:77], v[138:141], v[186:189], v[74:77]
	v_mfma_f32_16x16x32_bf16 v[74:77], v[142:145], v[190:193], v[74:77]
	v_mfma_f32_16x16x32_bf16 v[126:129], v[146:149], v[162:165], v[126:129]
	v_mfma_f32_16x16x32_bf16 v[126:129], v[150:153], v[166:169], v[126:129]
	v_mfma_f32_16x16x32_bf16 v[102:105], v[146:149], v[170:173], v[102:105]
	v_mfma_f32_16x16x32_bf16 v[102:105], v[150:153], v[174:177], v[102:105]
	v_mfma_f32_16x16x32_bf16 v[86:89], v[146:149], v[178:181], v[86:89]
	v_mfma_f32_16x16x32_bf16 v[86:89], v[150:153], v[182:185], v[86:89]
	v_mfma_f32_16x16x32_bf16 v[70:73], v[146:149], v[186:189], v[70:73]
	v_mfma_f32_16x16x32_bf16 v[70:73], v[150:153], v[190:193], v[70:73]
	v_mfma_f32_16x16x32_bf16 v[122:125], v[154:157], v[162:165], v[122:125]
	v_mfma_f32_16x16x32_bf16 v[122:125], v[158:161], v[166:169], v[122:125]
	v_mfma_f32_16x16x32_bf16 v[98:101], v[154:157], v[170:173], v[98:101]
	v_mfma_f32_16x16x32_bf16 v[98:101], v[158:161], v[174:177], v[98:101]
	v_mfma_f32_16x16x32_bf16 v[82:85], v[154:157], v[178:181], v[82:85]
	v_mfma_f32_16x16x32_bf16 v[82:85], v[158:161], v[182:185], v[82:85]
	v_mfma_f32_16x16x32_bf16 v[66:69], v[154:157], v[186:189], v[66:69]
	v_mfma_f32_16x16x32_bf16 v[66:69], v[158:161], v[190:193], v[66:69]
	s_barrier
	s_setprio 0
	s_add_i32 vcc_hi, vcc_hi, s6
	v_lshl_add_u64 v[210:211], s[38:39], 0, v[0:1]
	s_mov_b32 m0, vcc_hi
	ds_read_b128 v[162:165], v247 offset:16384
	ds_read_b128 v[166:169], v247 offset:17408
	ds_read_b128 v[170:173], v247 offset:18432
	ds_read_b128 v[174:177], v247 offset:19456
	ds_read_b128 v[178:181], v247 offset:20480
	ds_read_b128 v[182:185], v247 offset:21504
	ds_read_b128 v[186:189], v247 offset:22528
	ds_read_b128 v[190:193], v247 offset:23552
	global_load_lds_dwordx4 v[210:211], off
	s_add_i32 m0, vcc_hi, 0x2000
	v_lshl_add_u64 v[212:213], s[38:39], 0, v[204:205]
	s_add_u32 s38, s38, s58
	s_addc_u32 s39, s39, 0
	s_add_i32 s18, s18, s6
	global_load_lds_dwordx4 v[212:213], off
	v_lshl_add_u64 v[214:215], s[38:39], 0, v[0:1]
	s_mov_b32 m0, s18
	v_lshl_add_u64 v[216:217], s[38:39], 0, v[204:205]
	global_load_lds_dwordx4 v[214:215], off
	s_add_i32 m0, s18, 0x2000
	v_lshl_add_u64 v[218:219], s[46:47], 0, v[194:195]
	global_load_lds_dwordx4 v[216:217], off
	s_mov_b32 m0, s92
	v_lshl_add_u64 v[220:221], s[46:47], 0, v[202:203]
	global_load_lds_dwordx4 v[218:219], off
	s_mov_b32 m0, s93
	s_nop 0
	global_load_lds_dwordx4 v[220:221], off
	s_waitcnt vmcnt(8)
	s_waitcnt lgkmcnt(0)
	s_setprio 1
	s_barrier
; #define PG8_STAGE(bufoff, gbase, voff) do { _Pragma("unroll") for (int _i = 0; _i < 2; ++_i) \
;         __builtin_amdgcn_global_load_lds((const unsigned*)((const char*)(gbase) + (voff)[_i]), (PG8_LAS unsigned*)(lds + (bufoff) + ldsw + _i * 8192), 16, 0, 0); } while (0)
; #define PG8_LDA(dst, b, h) do { _Pragma("unroll") for (int m = 0; m < 4; ++m) _Pragma("unroll") for (int k = 0; k < 2; ++k) dst[m][k] = *(const PG8_LAS bf16x8*)(lds + PG8_SA(b, h) + aoff + m * 2048 + k * 1024); } while (0)
; #define PG8_LDB(dst, b, h) do { _Pragma("unroll") for (int n = 0; n < 2; ++n) _Pragma("unroll") for (int k = 0; k < 2; ++k) dst[n][k] = *(const PG8_LAS bf16x8*)(lds + PG8_SB(b, h) + boff + n * 2048 + k * 1024); } while (0)
; #define PG8_MMA(ai, bj, At, Bt) do { __builtin_amdgcn_s_setprio(1); _Pragma("unroll") for (int m = 0; m < 4; ++m) _Pragma("unroll") for (int n = 0; n < 2; ++n) _Pragma("unroll") for (int k = 0; k < 2; ++k) \
;         acc[ai][bj][m][n] = __builtin_amdgcn_mfma_f32_16x16x32_bf16(Bt[n][k], At[m][k], acc[ai][bj][m][n], 0, 0, 0); __builtin_amdgcn_s_setprio(0); } while (0)
; #define PG8_WAIT_V(n) asm volatile("s_waitcnt vmcnt(" #n ")" ::: "memory")
; #define PG8_WAIT_L(n) asm volatile("s_waitcnt lgkmcnt(" #n ")" ::: "memory")
; #define PG8_BAR __builtin_amdgcn_s_barrier()
; #define PG8_SCHED __builtin_amdgcn_sched_barrier(0)
; template <class Epi, class Sched, bool ALIGN_EPI = false, bool SP2 = false>
; __device__ __forceinline__ void gemm_phase(PG8_LAS unsigned char* lds, const Gemm g, const Sched& S, const Epi& E) {
;     ...
;             PG8_WAIT_V(8); PG8_WAIT_L(0); PG8_BAR; PG8_MMA(1, 0, At, B0); PG8_MMA(1, 1, At, B1); PG8_BAR; PG8_SCHED;
;             PG8_LDB(B0, 1, 0); PG8_LDB(B1, 1, 1); PG8_SCHED; PG8_LDA(At, 1, 0); PG8_STAGE(PG8_SA(0, 1), a2 + hstep, voffA);
;             PG8_WAIT_V(8); PG8_WAIT_L(0); PG8_BAR; PG8_MMA(0, 0, At, B0); PG8_MMA(0, 1, At, B1); PG8_BAR; PG8_SCHED;
	v_mfma_f32_16x16x32_bf16 v[62:65], v[110:113], v[162:165], v[62:65]
	v_mfma_f32_16x16x32_bf16 v[62:65], v[118:121], v[166:169], v[62:65]
	v_mfma_f32_16x16x32_bf16 v[46:49], v[110:113], v[170:173], v[46:49]
	v_mfma_f32_16x16x32_bf16 v[46:49], v[118:121], v[174:177], v[46:49]
	v_mfma_f32_16x16x32_bf16 v[30:33], v[110:113], v[178:181], v[30:33]
	v_mfma_f32_16x16x32_bf16 v[30:33], v[118:121], v[182:185], v[30:33]
	v_mfma_f32_16x16x32_bf16 v[14:17], v[110:113], v[186:189], v[14:17]
	v_mfma_f32_16x16x32_bf16 v[14:17], v[118:121], v[190:193], v[14:17]
	v_mfma_f32_16x16x32_bf16 v[58:61], v[138:141], v[162:165], v[58:61]
	v_mfma_f32_16x16x32_bf16 v[58:61], v[142:145], v[166:169], v[58:61]
	v_mfma_f32_16x16x32_bf16 v[42:45], v[138:141], v[170:173], v[42:45]
	v_mfma_f32_16x16x32_bf16 v[42:45], v[142:145], v[174:177], v[42:45]
	v_mfma_f32_16x16x32_bf16 v[26:29], v[138:141], v[178:181], v[26:29]
	v_mfma_f32_16x16x32_bf16 v[26:29], v[142:145], v[182:185], v[26:29]
	v_mfma_f32_16x16x32_bf16 v[10:13], v[138:141], v[186:189], v[10:13]
	v_mfma_f32_16x16x32_bf16 v[10:13], v[142:145], v[190:193], v[10:13]
	v_mfma_f32_16x16x32_bf16 v[54:57], v[146:149], v[162:165], v[54:57]
	v_mfma_f32_16x16x32_bf16 v[54:57], v[150:153], v[166:169], v[54:57]
	v_mfma_f32_16x16x32_bf16 v[38:41], v[146:149], v[170:173], v[38:41]
	v_mfma_f32_16x16x32_bf16 v[38:41], v[150:153], v[174:177], v[38:41]
	v_mfma_f32_16x16x32_bf16 v[22:25], v[146:149], v[178:181], v[22:25]
	v_mfma_f32_16x16x32_bf16 v[22:25], v[150:153], v[182:185], v[22:25]
	v_mfma_f32_16x16x32_bf16 v[6:9], v[146:149], v[186:189], v[6:9]
	v_mfma_f32_16x16x32_bf16 v[6:9], v[150:153], v[190:193], v[6:9]
	v_mfma_f32_16x16x32_bf16 v[50:53], v[154:157], v[162:165], v[50:53]
	v_mfma_f32_16x16x32_bf16 v[50:53], v[158:161], v[166:169], v[50:53]
	v_mfma_f32_16x16x32_bf16 v[34:37], v[154:157], v[170:173], v[34:37]
	v_mfma_f32_16x16x32_bf16 v[34:37], v[158:161], v[174:177], v[34:37]
	v_mfma_f32_16x16x32_bf16 v[18:21], v[154:157], v[178:181], v[18:21]
	v_mfma_f32_16x16x32_bf16 v[18:21], v[158:161], v[182:185], v[18:21]
	v_mfma_f32_16x16x32_bf16 v[2:5], v[154:157], v[186:189], v[2:5]
	v_mfma_f32_16x16x32_bf16 v[2:5], v[158:161], v[190:193], v[2:5]
	s_barrier
	s_setprio 0
	s_add_i32 s18, 0, 0x18000
	s_add_i32 vcc_hi, 0, 0x1c000
	v_add_u32_e32 v142, s18, v245
	v_add_u32_e32 v158, vcc_hi, v245
	ds_read_b128 v[110:113], v142
	ds_read_b128 v[118:121], v142 offset:1024
	ds_read_b128 v[138:141], v142 offset:2048
	ds_read_b128 v[142:145], v142 offset:3072
	ds_read_b128 v[146:149], v158
	ds_read_b128 v[150:153], v158 offset:1024
	ds_read_b128 v[154:157], v158 offset:2048
	ds_read_b128 v[158:161], v158 offset:3072
	s_add_u32 s38, s46, s58
	s_addc_u32 s39, s47, 0
	s_mov_b32 m0, s94
	v_lshl_add_u64 v[222:223], s[38:39], 0, v[194:195]
	ds_read_b128 v[162:165], v247 offset:32768
	ds_read_b128 v[166:169], v247 offset:33792
	ds_read_b128 v[170:173], v247 offset:34816
	ds_read_b128 v[174:177], v247 offset:35840
	ds_read_b128 v[178:181], v247 offset:36864
	ds_read_b128 v[182:185], v247 offset:37888
	ds_read_b128 v[186:189], v247 offset:38912
	ds_read_b128 v[190:193], v247 offset:39936
	global_load_lds_dwordx4 v[222:223], off
	v_lshl_add_u64 v[222:223], s[38:39], 0, v[202:203]
	s_mov_b32 m0, s95
	s_nop 0
	global_load_lds_dwordx4 v[222:223], off
	s_waitcnt vmcnt(8)
	s_waitcnt lgkmcnt(0)
	s_setprio 1
	s_barrier
	v_mfma_f32_16x16x32_bf16 v[130:133], v[110:113], v[162:165], v[130:133]
	v_mfma_f32_16x16x32_bf16 v[130:133], v[118:121], v[166:169], v[130:133]
	v_mfma_f32_16x16x32_bf16 v[114:117], v[110:113], v[170:173], v[114:117]
	v_mfma_f32_16x16x32_bf16 v[114:117], v[118:121], v[174:177], v[114:117]
	v_mfma_f32_16x16x32_bf16 v[94:97], v[110:113], v[178:181], v[94:97]
	v_mfma_f32_16x16x32_bf16 v[94:97], v[118:121], v[182:185], v[94:97]
	v_mfma_f32_16x16x32_bf16 v[78:81], v[110:113], v[186:189], v[78:81]
	v_mfma_f32_16x16x32_bf16 v[78:81], v[118:121], v[190:193], v[78:81]
	v_mfma_f32_16x16x32_bf16 v[134:137], v[138:141], v[162:165], v[134:137]
	v_mfma_f32_16x16x32_bf16 v[134:137], v[142:145], v[166:169], v[134:137]
	v_mfma_f32_16x16x32_bf16 v[106:109], v[138:141], v[170:173], v[106:109]
	v_mfma_f32_16x16x32_bf16 v[106:109], v[142:145], v[174:177], v[106:109]
	v_mfma_f32_16x16x32_bf16 v[90:93], v[138:141], v[178:181], v[90:93]
	v_mfma_f32_16x16x32_bf16 v[90:93], v[142:145], v[182:185], v[90:93]
	v_mfma_f32_16x16x32_bf16 v[74:77], v[138:141], v[186:189], v[74:77]
	v_mfma_f32_16x16x32_bf16 v[74:77], v[142:145], v[190:193], v[74:77]
	v_mfma_f32_16x16x32_bf16 v[126:129], v[146:149], v[162:165], v[126:129]
	v_mfma_f32_16x16x32_bf16 v[126:129], v[150:153], v[166:169], v[126:129]
	v_mfma_f32_16x16x32_bf16 v[102:105], v[146:149], v[170:173], v[102:105]
	v_mfma_f32_16x16x32_bf16 v[102:105], v[150:153], v[174:177], v[102:105]
	v_mfma_f32_16x16x32_bf16 v[86:89], v[146:149], v[178:181], v[86:89]
	v_mfma_f32_16x16x32_bf16 v[86:89], v[150:153], v[182:185], v[86:89]
	v_mfma_f32_16x16x32_bf16 v[70:73], v[146:149], v[186:189], v[70:73]
	v_mfma_f32_16x16x32_bf16 v[70:73], v[150:153], v[190:193], v[70:73]
	v_mfma_f32_16x16x32_bf16 v[122:125], v[154:157], v[162:165], v[122:125]
	v_mfma_f32_16x16x32_bf16 v[122:125], v[158:161], v[166:169], v[122:125]
	v_mfma_f32_16x16x32_bf16 v[98:101], v[154:157], v[170:173], v[98:101]
	v_mfma_f32_16x16x32_bf16 v[98:101], v[158:161], v[174:177], v[98:101]
	v_mfma_f32_16x16x32_bf16 v[82:85], v[154:157], v[178:181], v[82:85]
	v_mfma_f32_16x16x32_bf16 v[82:85], v[158:161], v[182:185], v[82:85]
	v_mfma_f32_16x16x32_bf16 v[66:69], v[154:157], v[186:189], v[66:69]
	v_mfma_f32_16x16x32_bf16 v[66:69], v[158:161], v[190:193], v[66:69]
	s_barrier
; #define PG8_STAGE(bufoff, gbase, voff) do { _Pragma("unroll") for (int _i = 0; _i < 2; ++_i) \
;         __builtin_amdgcn_global_load_lds((const unsigned*)((const char*)(gbase) + (voff)[_i]), (PG8_LAS unsigned*)(lds + (bufoff) + ldsw + _i * 8192), 16, 0, 0); } while (0)
; #define PG8_LDA(dst, b, h) do { _Pragma("unroll") for (int m = 0; m < 4; ++m) _Pragma("unroll") for (int k = 0; k < 2; ++k) dst[m][k] = *(const PG8_LAS bf16x8*)(lds + PG8_SA(b, h) + aoff + m * 2048 + k * 1024); } while (0)
; #define PG8_MMA(ai, bj, At, Bt) do { __builtin_amdgcn_s_setprio(1); _Pragma("unroll") for (int m = 0; m < 4; ++m) _Pragma("unroll") for (int n = 0; n < 2; ++n) _Pragma("unroll") for (int k = 0; k < 2; ++k) \
;         acc[ai][bj][m][n] = __builtin_amdgcn_mfma_f32_16x16x32_bf16(Bt[n][k], At[m][k], acc[ai][bj][m][n], 0, 0, 0); __builtin_amdgcn_s_setprio(0); } while (0)
; #define PG8_WAIT_V(n) asm volatile("s_waitcnt vmcnt(" #n ")" ::: "memory")
; #define PG8_WAIT_L(n) asm volatile("s_waitcnt lgkmcnt(" #n ")" ::: "memory")
; #define PG8_BAR __builtin_amdgcn_s_barrier()
; #define PG8_SCHED __builtin_amdgcn_sched_barrier(0)
; template <class Epi, class Sched, bool ALIGN_EPI = false, bool SP2 = false>
; __device__ __forceinline__ void gemm_phase(PG8_LAS unsigned char* lds, const Gemm g, const Sched& S, const Epi& E) {
;     ...
;             PG8_LDA(At, 1, 1); PG8_STAGE(PG8_SB(1, 0), b3, voffB); PG8_STAGE(PG8_SB(1, 1), b3 + hstep, voffB); PG8_STAGE(PG8_SA(1, 0), a3, voffA);
;             PG8_WAIT_V(8); PG8_WAIT_L(0); PG8_BAR; PG8_MMA(1, 0, At, B0); PG8_MMA(1, 1, At, B1); PG8_BAR; PG8_SCHED;
;     ...
;         if constexpr (ALIGN_EPI) { if (wr == 0) PG8_BAR; }
	s_setprio 0
	s_add_i32 s18, s18, s6
	v_lshl_add_u64 v[210:211], v[210:211], 0, s[30:31]
	s_mov_b32 m0, s18
	ds_read_b128 v[162:165], v247 offset:49152
	ds_read_b128 v[166:169], v247 offset:50176
	ds_read_b128 v[170:173], v247 offset:51200
	ds_read_b128 v[174:177], v247 offset:52224
	ds_read_b128 v[178:181], v247 offset:53248
	ds_read_b128 v[182:185], v247 offset:54272
	ds_read_b128 v[186:189], v247 offset:55296
	ds_read_b128 v[190:193], v247 offset:56320
	global_load_lds_dwordx4 v[210:211], off
	v_lshl_add_u64 v[210:211], v[212:213], 0, s[30:31]
	s_add_i32 m0, s18, 0x2000
	s_add_i32 s18, vcc_hi, s6
	global_load_lds_dwordx4 v[210:211], off
	v_lshl_add_u64 v[210:211], v[214:215], 0, s[30:31]
	s_mov_b32 m0, s18
	s_nop 0
	global_load_lds_dwordx4 v[210:211], off
	v_lshl_add_u64 v[210:211], v[216:217], 0, s[30:31]
	s_add_i32 m0, s18, 0x2000
	s_nop 0
	global_load_lds_dwordx4 v[210:211], off
	v_lshl_add_u64 v[210:211], v[218:219], 0, s[30:31]
	s_mov_b32 m0, s97
	s_nop 0
	global_load_lds_dwordx4 v[210:211], off
	v_lshl_add_u64 v[210:211], v[220:221], 0, s[30:31]
	s_mov_b32 m0, s98
	s_nop 0
	global_load_lds_dwordx4 v[210:211], off
	s_waitcnt vmcnt(8)
	s_waitcnt lgkmcnt(0)
	s_setprio 1
	s_barrier
	v_mfma_f32_16x16x32_bf16 v[62:65], v[110:113], v[162:165], v[62:65]
	v_mfma_f32_16x16x32_bf16 v[62:65], v[118:121], v[166:169], v[62:65]
	v_mfma_f32_16x16x32_bf16 v[46:49], v[110:113], v[170:173], v[46:49]
	v_mfma_f32_16x16x32_bf16 v[46:49], v[118:121], v[174:177], v[46:49]
	v_mfma_f32_16x16x32_bf16 v[30:33], v[110:113], v[178:181], v[30:33]
	v_mfma_f32_16x16x32_bf16 v[30:33], v[118:121], v[182:185], v[30:33]
	v_mfma_f32_16x16x32_bf16 v[14:17], v[110:113], v[186:189], v[14:17]
	v_mfma_f32_16x16x32_bf16 v[14:17], v[118:121], v[190:193], v[14:17]
	v_mfma_f32_16x16x32_bf16 v[58:61], v[138:141], v[162:165], v[58:61]
	v_mfma_f32_16x16x32_bf16 v[58:61], v[142:145], v[166:169], v[58:61]
	v_mfma_f32_16x16x32_bf16 v[42:45], v[138:141], v[170:173], v[42:45]
	v_mfma_f32_16x16x32_bf16 v[42:45], v[142:145], v[174:177], v[42:45]
	v_mfma_f32_16x16x32_bf16 v[26:29], v[138:141], v[178:181], v[26:29]
	v_mfma_f32_16x16x32_bf16 v[26:29], v[142:145], v[182:185], v[26:29]
	v_mfma_f32_16x16x32_bf16 v[10:13], v[138:141], v[186:189], v[10:13]
	v_mfma_f32_16x16x32_bf16 v[10:13], v[142:145], v[190:193], v[10:13]
	v_mfma_f32_16x16x32_bf16 v[54:57], v[146:149], v[162:165], v[54:57]
	v_mfma_f32_16x16x32_bf16 v[54:57], v[150:153], v[166:169], v[54:57]
	v_mfma_f32_16x16x32_bf16 v[38:41], v[146:149], v[170:173], v[38:41]
	v_mfma_f32_16x16x32_bf16 v[38:41], v[150:153], v[174:177], v[38:41]
	v_mfma_f32_16x16x32_bf16 v[22:25], v[146:149], v[178:181], v[22:25]
	v_mfma_f32_16x16x32_bf16 v[22:25], v[150:153], v[182:185], v[22:25]
	v_mfma_f32_16x16x32_bf16 v[6:9], v[146:149], v[186:189], v[6:9]
	v_mfma_f32_16x16x32_bf16 v[6:9], v[150:153], v[190:193], v[6:9]
	v_mfma_f32_16x16x32_bf16 v[50:53], v[154:157], v[162:165], v[50:53]
	v_mfma_f32_16x16x32_bf16 v[50:53], v[158:161], v[166:169], v[50:53]
	v_mfma_f32_16x16x32_bf16 v[34:37], v[154:157], v[170:173], v[34:37]
	v_mfma_f32_16x16x32_bf16 v[34:37], v[158:161], v[174:177], v[34:37]
	v_mfma_f32_16x16x32_bf16 v[18:21], v[154:157], v[178:181], v[18:21]
	v_mfma_f32_16x16x32_bf16 v[18:21], v[158:161], v[182:185], v[18:21]
	v_mfma_f32_16x16x32_bf16 v[2:5], v[154:157], v[186:189], v[2:5]
	v_mfma_f32_16x16x32_bf16 v[2:5], v[158:161], v[190:193], v[2:5]
	s_barrier
	s_setprio 0
	s_add_u32 s48, s48, 0x100
	s_addc_u32 s49, s49, 0
	s_add_u32 s50, s50, 0x100
	s_addc_u32 s51, s51, 0
	s_cmp_ge_u32 vcc_lo, s96
	s_mov_b32 s46, vcc_lo
	s_cbranch_scc0 .LBB0_274
	s_and_b64 vcc, exec, s[72:73]
	s_cbranch_vccz .LBB0_277
	s_barrier

; #define PG8_STAGE(bufoff, gbase, voff) do { _Pragma("unroll") for (int _i = 0; _i < 2; ++_i) \
;         __builtin_amdgcn_global_load_lds((const unsigned*)((const char*)(gbase) + (voff)[_i]), (PG8_LAS unsigned*)(lds + (bufoff) + ldsw + _i * 8192), 16, 0, 0); } while (0)
; #define PG8_LDA(dst, b, h) do { _Pragma("unroll") for (int m = 0; m < 4; ++m) _Pragma("unroll") for (int k = 0; k < 2; ++k) dst[m][k] = *(const PG8_LAS bf16x8*)(lds + PG8_SA(b, h) + aoff + m * 2048 + k * 1024); } while (0)
; #define PG8_LDB(dst, b, h) do { _Pragma("unroll") for (int n = 0; n < 2; ++n) _Pragma("unroll") for (int k = 0; k < 2; ++k) dst[n][k] = *(const PG8_LAS bf16x8*)(lds + PG8_SB(b, h) + boff + n * 2048 + k * 1024); } while (0)
; #define PG8_MMA(ai, bj, At, Bt) do { __builtin_amdgcn_s_setprio(1); _Pragma("unroll") for (int m = 0; m < 4; ++m) _Pragma("unroll") for (int n = 0; n < 2; ++n) _Pragma("unroll") for (int k = 0; k < 2; ++k) \
;         acc[ai][bj][m][n] = __builtin_amdgcn_mfma_f32_16x16x32_bf16(Bt[n][k], At[m][k], acc[ai][bj][m][n], 0, 0, 0); __builtin_amdgcn_s_setprio(0); } while (0)
; #define PG8_WAIT_V(n) asm volatile("s_waitcnt vmcnt(" #n ")" ::: "memory")
; #define PG8_WAIT_L(n) asm volatile("s_waitcnt lgkmcnt(" #n ")" ::: "memory")
; template <class Epi, class Sched, bool ALIGN_EPI = false, bool SP2 = false>
; __device__ __forceinline__ void gemm_phase(PG8_LAS unsigned char* lds, const Gemm g, const Sched& S, const Epi& E) {
;     ...
;             const bool last = (t == nt - 2);
;             const char* a1 = cA + (size_t)(t + 1) * kstep;
;             const char* a2 = last ? nA : cA + (size_t)(t + 2) * kstep; const char* b2 = last ? nB : cB + (size_t)(t + 2) * kstep;
;             const char* a3 = a2 + kstep; const char* b3 = b2 + kstep;
;             if (last && has_next) S.a_ready(nxt);
;             if constexpr (SP2) {
;             PG8_LDB(B0, 0, 0); PG8_LDB(B1, 0, 1); PG8_SCHED; PG8_LDA(At, 0, 0); PG8_STAGE(PG8_SA(1, 1), a1 + hstep, voffA);
;             PG8_WAIT_V(8); PG8_WAIT_L(0); PG8_BAR; PG8_MMA(0, 0, At, B0); PG8_MMA(0, 1, At, B1); PG8_BAR; PG8_SCHED;
;             PG8_LDA(At, 0, 1); PG8_STAGE(PG8_SB(0, 0), b2, voffB); PG8_STAGE(PG8_SB(0, 1), b2 + hstep, voffB); PG8_STAGE(PG8_SA(0, 0), a2, voffA);
;             PG8_WAIT_V(8); PG8_WAIT_L(0); PG8_BAR; PG8_MMA(1, 0, At, B0); PG8_MMA(1, 1, At, B1); PG8_BAR; PG8_SCHED;
.LBB0_408:
	s_add_u32 s38, s48, 0xfffc0080
	s_addc_u32 s39, s49, -1
	s_add_i32 s85, 0, 0x10000
	s_cmp_eq_u32 s84, 12
	s_cselect_b32 s73, s21, s39
	s_cselect_b32 s72, s27, s38
	v_add_u32_e32 v0, s85, v167
	s_cselect_b32 s47, s29, s69
	s_cselect_b32 s46, s33, s53
	s_add_i32 s38, 0, 0x14000
	ds_read_b128 v[142:145], v0
	ds_read_b128 v[146:149], v0 offset:1024
	ds_read_b128 v[150:153], v0 offset:2048
	ds_read_b128 v[154:157], v0 offset:3072
	v_add_u32_e32 v0, s38, v167
	ds_read_b128 v[158:161], v0
	ds_read_b128 v[162:165], v0 offset:1024
	ds_read_b128 v[172:175], v0 offset:2048
	ds_read_b128 v[176:179], v0 offset:3072
	v_lshl_add_u64 v[218:219], s[48:49], 0, v[138:139]
	s_add_i32 m0, s76, 0xc000
	ds_read_b128 v[180:183], v170
	ds_read_b128 v[184:187], v170 offset:1024
	ds_read_b128 v[188:191], v170 offset:2048
	ds_read_b128 v[192:195], v170 offset:3072
	ds_read_b128 v[202:205], v170 offset:4096
	ds_read_b128 v[206:209], v170 offset:5120
	ds_read_b128 v[210:213], v170 offset:6144
	ds_read_b128 v[214:217], v170 offset:7168
	global_load_lds_dwordx4 v[218:219], off
	v_lshl_add_u64 v[218:219], s[48:49], 0, v[140:141]
	s_add_i32 m0, s76, 0xe000
	s_nop 0
	global_load_lds_dwordx4 v[218:219], off
	s_waitcnt vmcnt(8)
	s_waitcnt lgkmcnt(0)
	s_setprio 1
	s_barrier
	v_mfma_f32_16x16x32_bf16 v[122:125], v[142:145], v[180:183], v[122:125]
	v_mfma_f32_16x16x32_bf16 v[122:125], v[146:149], v[184:187], v[122:125]
	v_mfma_f32_16x16x32_bf16 v[106:109], v[142:145], v[188:191], v[106:109]
	v_mfma_f32_16x16x32_bf16 v[106:109], v[146:149], v[192:195], v[106:109]
	v_mfma_f32_16x16x32_bf16 v[90:93], v[142:145], v[202:205], v[90:93]
	v_mfma_f32_16x16x32_bf16 v[90:93], v[146:149], v[206:209], v[90:93]
	v_mfma_f32_16x16x32_bf16 v[74:77], v[142:145], v[210:213], v[74:77]
	v_mfma_f32_16x16x32_bf16 v[74:77], v[146:149], v[214:217], v[74:77]
	v_mfma_f32_16x16x32_bf16 v[126:129], v[150:153], v[180:183], v[126:129]
	v_mfma_f32_16x16x32_bf16 v[126:129], v[154:157], v[184:187], v[126:129]
	v_mfma_f32_16x16x32_bf16 v[110:113], v[150:153], v[188:191], v[110:113]
	v_mfma_f32_16x16x32_bf16 v[110:113], v[154:157], v[192:195], v[110:113]
	v_mfma_f32_16x16x32_bf16 v[94:97], v[150:153], v[202:205], v[94:97]
	v_mfma_f32_16x16x32_bf16 v[94:97], v[154:157], v[206:209], v[94:97]
	v_mfma_f32_16x16x32_bf16 v[78:81], v[150:153], v[210:213], v[78:81]
	v_mfma_f32_16x16x32_bf16 v[78:81], v[154:157], v[214:217], v[78:81]
	v_mfma_f32_16x16x32_bf16 v[114:117], v[158:161], v[180:183], v[114:117]
	v_mfma_f32_16x16x32_bf16 v[114:117], v[162:165], v[184:187], v[114:117]
	v_mfma_f32_16x16x32_bf16 v[98:101], v[158:161], v[188:191], v[98:101]
	v_mfma_f32_16x16x32_bf16 v[98:101], v[162:165], v[192:195], v[98:101]
	v_mfma_f32_16x16x32_bf16 v[82:85], v[158:161], v[202:205], v[82:85]
	v_mfma_f32_16x16x32_bf16 v[82:85], v[162:165], v[206:209], v[82:85]
	v_mfma_f32_16x16x32_bf16 v[66:69], v[158:161], v[210:213], v[66:69]
	v_mfma_f32_16x16x32_bf16 v[66:69], v[162:165], v[214:217], v[66:69]
	v_mfma_f32_16x16x32_bf16 v[118:121], v[172:175], v[180:183], v[118:121]
	v_mfma_f32_16x16x32_bf16 v[118:121], v[176:179], v[184:187], v[118:121]
	v_mfma_f32_16x16x32_bf16 v[102:105], v[172:175], v[188:191], v[102:105]
	v_mfma_f32_16x16x32_bf16 v[102:105], v[176:179], v[192:195], v[102:105]
	v_mfma_f32_16x16x32_bf16 v[86:89], v[172:175], v[202:205], v[86:89]
	v_mfma_f32_16x16x32_bf16 v[86:89], v[176:179], v[206:209], v[86:89]
	v_mfma_f32_16x16x32_bf16 v[70:73], v[172:175], v[210:213], v[70:73]
	v_mfma_f32_16x16x32_bf16 v[70:73], v[176:179], v[214:217], v[70:73]
	s_barrier
	s_setprio 0
	s_add_i32 s39, s85, s75
	v_lshl_add_u64 v[218:219], s[46:47], 0, v[134:135]
	s_mov_b32 m0, s39
	ds_read_b128 v[180:183], v170 offset:16384
	ds_read_b128 v[184:187], v170 offset:17408
	ds_read_b128 v[188:191], v170 offset:18432
	ds_read_b128 v[192:195], v170 offset:19456
	ds_read_b128 v[202:205], v170 offset:20480
	ds_read_b128 v[206:209], v170 offset:21504
	ds_read_b128 v[210:213], v170 offset:22528
	ds_read_b128 v[214:217], v170 offset:23552
	global_load_lds_dwordx4 v[218:219], off
	s_add_i32 m0, s39, 0x2000
	s_add_u32 s92, s46, 0x40000
	v_lshl_add_u64 v[220:221], s[46:47], 0, v[130:131]
	s_addc_u32 s93, s47, 0
	s_add_i32 s38, s38, s75
	global_load_lds_dwordx4 v[220:221], off
	v_lshl_add_u64 v[222:223], s[92:93], 0, v[134:135]
	s_mov_b32 m0, s38
	v_lshl_add_u64 v[224:225], s[72:73], 0, v[132:133]
	global_load_lds_dwordx4 v[222:223], off
	v_lshl_add_u64 v[222:223], s[92:93], 0, v[130:131]
	s_add_i32 m0, s38, 0x2000
	s_nop 0
	global_load_lds_dwordx4 v[222:223], off
	v_lshl_add_u64 v[222:223], s[72:73], 0, v[136:137]
	s_mov_b32 m0, s76
	s_nop 0
	global_load_lds_dwordx4 v[222:223], off
	s_mov_b32 m0, s77
	s_nop 0
	global_load_lds_dwordx4 v[224:225], off
	s_waitcnt vmcnt(8)
	s_waitcnt lgkmcnt(0)
	s_setprio 1
	s_barrier
; #define PG8_STAGE(bufoff, gbase, voff) do { _Pragma("unroll") for (int _i = 0; _i < 2; ++_i) \
;         __builtin_amdgcn_global_load_lds((const unsigned*)((const char*)(gbase) + (voff)[_i]), (PG8_LAS unsigned*)(lds + (bufoff) + ldsw + _i * 8192), 16, 0, 0); } while (0)
; #define PG8_LDA(dst, b, h) do { _Pragma("unroll") for (int m = 0; m < 4; ++m) _Pragma("unroll") for (int k = 0; k < 2; ++k) dst[m][k] = *(const PG8_LAS bf16x8*)(lds + PG8_SA(b, h) + aoff + m * 2048 + k * 1024); } while (0)
; #define PG8_LDB(dst, b, h) do { _Pragma("unroll") for (int n = 0; n < 2; ++n) _Pragma("unroll") for (int k = 0; k < 2; ++k) dst[n][k] = *(const PG8_LAS bf16x8*)(lds + PG8_SB(b, h) + boff + n * 2048 + k * 1024); } while (0)
; #define PG8_MMA(ai, bj, At, Bt) do { __builtin_amdgcn_s_setprio(1); _Pragma("unroll") for (int m = 0; m < 4; ++m) _Pragma("unroll") for (int n = 0; n < 2; ++n) _Pragma("unroll") for (int k = 0; k < 2; ++k) \
;         acc[ai][bj][m][n] = __builtin_amdgcn_mfma_f32_16x16x32_bf16(Bt[n][k], At[m][k], acc[ai][bj][m][n], 0, 0, 0); __builtin_amdgcn_s_setprio(0); } while (0)
; #define PG8_WAIT_V(n) asm volatile("s_waitcnt vmcnt(" #n ")" ::: "memory")
; #define PG8_WAIT_L(n) asm volatile("s_waitcnt lgkmcnt(" #n ")" ::: "memory")
; #define PG8_BAR __builtin_amdgcn_s_barrier()
; #define PG8_SCHED __builtin_amdgcn_sched_barrier(0)
; template <class Epi, class Sched, bool ALIGN_EPI = false, bool SP2 = false>
; __device__ __forceinline__ void gemm_phase(PG8_LAS unsigned char* lds, const Gemm g, const Sched& S, const Epi& E) {
;     ...
;             PG8_WAIT_V(8); PG8_WAIT_L(0); PG8_BAR; PG8_MMA(1, 0, At, B0); PG8_MMA(1, 1, At, B1); PG8_BAR; PG8_SCHED;
;             PG8_LDB(B0, 1, 0); PG8_LDB(B1, 1, 1); PG8_SCHED; PG8_LDA(At, 1, 0); PG8_STAGE(PG8_SA(0, 1), a2 + hstep, voffA);
;             PG8_WAIT_V(8); PG8_WAIT_L(0); PG8_BAR; PG8_MMA(0, 0, At, B0); PG8_MMA(0, 1, At, B1); PG8_BAR; PG8_SCHED;
	v_mfma_f32_16x16x32_bf16 v[58:61], v[142:145], v[180:183], v[58:61]
	v_mfma_f32_16x16x32_bf16 v[58:61], v[146:149], v[184:187], v[58:61]
	v_mfma_f32_16x16x32_bf16 v[42:45], v[142:145], v[188:191], v[42:45]
	v_mfma_f32_16x16x32_bf16 v[42:45], v[146:149], v[192:195], v[42:45]
	v_mfma_f32_16x16x32_bf16 v[26:29], v[142:145], v[202:205], v[26:29]
	v_mfma_f32_16x16x32_bf16 v[26:29], v[146:149], v[206:209], v[26:29]
	v_mfma_f32_16x16x32_bf16 v[10:13], v[142:145], v[210:213], v[10:13]
	v_mfma_f32_16x16x32_bf16 v[10:13], v[146:149], v[214:217], v[10:13]
	v_mfma_f32_16x16x32_bf16 v[62:65], v[150:153], v[180:183], v[62:65]
	v_mfma_f32_16x16x32_bf16 v[62:65], v[154:157], v[184:187], v[62:65]
	v_mfma_f32_16x16x32_bf16 v[46:49], v[150:153], v[188:191], v[46:49]
	v_mfma_f32_16x16x32_bf16 v[46:49], v[154:157], v[192:195], v[46:49]
	v_mfma_f32_16x16x32_bf16 v[30:33], v[150:153], v[202:205], v[30:33]
	v_mfma_f32_16x16x32_bf16 v[30:33], v[154:157], v[206:209], v[30:33]
	v_mfma_f32_16x16x32_bf16 v[14:17], v[150:153], v[210:213], v[14:17]
	v_mfma_f32_16x16x32_bf16 v[14:17], v[154:157], v[214:217], v[14:17]
	v_mfma_f32_16x16x32_bf16 v[50:53], v[158:161], v[180:183], v[50:53]
	v_mfma_f32_16x16x32_bf16 v[50:53], v[162:165], v[184:187], v[50:53]
	v_mfma_f32_16x16x32_bf16 v[34:37], v[158:161], v[188:191], v[34:37]
	v_mfma_f32_16x16x32_bf16 v[34:37], v[162:165], v[192:195], v[34:37]
	v_mfma_f32_16x16x32_bf16 v[18:21], v[158:161], v[202:205], v[18:21]
	v_mfma_f32_16x16x32_bf16 v[18:21], v[162:165], v[206:209], v[18:21]
	v_mfma_f32_16x16x32_bf16 v[2:5], v[158:161], v[210:213], v[2:5]
	v_mfma_f32_16x16x32_bf16 v[2:5], v[162:165], v[214:217], v[2:5]
	v_mfma_f32_16x16x32_bf16 v[54:57], v[172:175], v[180:183], v[54:57]
	v_mfma_f32_16x16x32_bf16 v[54:57], v[176:179], v[184:187], v[54:57]
	v_mfma_f32_16x16x32_bf16 v[38:41], v[172:175], v[188:191], v[38:41]
	v_mfma_f32_16x16x32_bf16 v[38:41], v[176:179], v[192:195], v[38:41]
	v_mfma_f32_16x16x32_bf16 v[22:25], v[172:175], v[202:205], v[22:25]
	v_mfma_f32_16x16x32_bf16 v[22:25], v[176:179], v[206:209], v[22:25]
	v_mfma_f32_16x16x32_bf16 v[6:9], v[172:175], v[210:213], v[6:9]
	v_mfma_f32_16x16x32_bf16 v[6:9], v[176:179], v[214:217], v[6:9]
	s_barrier
	s_setprio 0
	s_add_i32 s38, 0, 0x18000
	v_add_u32_e32 v0, s38, v167
	s_add_i32 s39, 0, 0x1c000
	ds_read_b128 v[142:145], v0
	ds_read_b128 v[146:149], v0 offset:1024
	ds_read_b128 v[150:153], v0 offset:2048
	ds_read_b128 v[154:157], v0 offset:3072
	v_add_u32_e32 v0, s39, v167
	ds_read_b128 v[158:161], v0
	ds_read_b128 v[162:165], v0 offset:1024
	ds_read_b128 v[172:175], v0 offset:2048
	ds_read_b128 v[176:179], v0 offset:3072
	s_add_u32 s72, s72, 0x40000
	s_addc_u32 s73, s73, 0
	s_mov_b32 m0, s78
	v_lshl_add_u64 v[226:227], s[72:73], 0, v[136:137]
	ds_read_b128 v[180:183], v170 offset:32768
	ds_read_b128 v[184:187], v170 offset:33792
	ds_read_b128 v[188:191], v170 offset:34816
	ds_read_b128 v[192:195], v170 offset:35840
	ds_read_b128 v[202:205], v170 offset:36864
	ds_read_b128 v[206:209], v170 offset:37888
	ds_read_b128 v[210:213], v170 offset:38912
	ds_read_b128 v[214:217], v170 offset:39936
	global_load_lds_dwordx4 v[226:227], off
	v_lshl_add_u64 v[226:227], s[72:73], 0, v[132:133]
	s_mov_b32 m0, s79
	s_nop 0
	global_load_lds_dwordx4 v[226:227], off
	s_waitcnt vmcnt(8)
	s_waitcnt lgkmcnt(0)
	s_setprio 1
	s_barrier
	v_mfma_f32_16x16x32_bf16 v[122:125], v[142:145], v[180:183], v[122:125]
	v_mfma_f32_16x16x32_bf16 v[122:125], v[146:149], v[184:187], v[122:125]
	v_mfma_f32_16x16x32_bf16 v[106:109], v[142:145], v[188:191], v[106:109]
	v_mfma_f32_16x16x32_bf16 v[106:109], v[146:149], v[192:195], v[106:109]
	v_mfma_f32_16x16x32_bf16 v[90:93], v[142:145], v[202:205], v[90:93]
	v_mfma_f32_16x16x32_bf16 v[90:93], v[146:149], v[206:209], v[90:93]
	v_mfma_f32_16x16x32_bf16 v[74:77], v[142:145], v[210:213], v[74:77]
	v_mfma_f32_16x16x32_bf16 v[74:77], v[146:149], v[214:217], v[74:77]
	v_mfma_f32_16x16x32_bf16 v[126:129], v[150:153], v[180:183], v[126:129]
	v_mfma_f32_16x16x32_bf16 v[126:129], v[154:157], v[184:187], v[126:129]
	v_mfma_f32_16x16x32_bf16 v[110:113], v[150:153], v[188:191], v[110:113]
	v_mfma_f32_16x16x32_bf16 v[110:113], v[154:157], v[192:195], v[110:113]
	v_mfma_f32_16x16x32_bf16 v[94:97], v[150:153], v[202:205], v[94:97]
	v_mfma_f32_16x16x32_bf16 v[94:97], v[154:157], v[206:209], v[94:97]
	v_mfma_f32_16x16x32_bf16 v[78:81], v[150:153], v[210:213], v[78:81]
	v_mfma_f32_16x16x32_bf16 v[78:81], v[154:157], v[214:217], v[78:81]
	v_mfma_f32_16x16x32_bf16 v[114:117], v[158:161], v[180:183], v[114:117]
	v_mfma_f32_16x16x32_bf16 v[114:117], v[162:165], v[184:187], v[114:117]
	v_mfma_f32_16x16x32_bf16 v[98:101], v[158:161], v[188:191], v[98:101]
	v_mfma_f32_16x16x32_bf16 v[98:101], v[162:165], v[192:195], v[98:101]
	v_mfma_f32_16x16x32_bf16 v[82:85], v[158:161], v[202:205], v[82:85]
	v_mfma_f32_16x16x32_bf16 v[82:85], v[162:165], v[206:209], v[82:85]
	v_mfma_f32_16x16x32_bf16 v[66:69], v[158:161], v[210:213], v[66:69]
	v_mfma_f32_16x16x32_bf16 v[66:69], v[162:165], v[214:217], v[66:69]
	v_mfma_f32_16x16x32_bf16 v[118:121], v[172:175], v[180:183], v[118:121]
	v_mfma_f32_16x16x32_bf16 v[118:121], v[176:179], v[184:187], v[118:121]
	v_mfma_f32_16x16x32_bf16 v[102:105], v[172:175], v[188:191], v[102:105]
	v_mfma_f32_16x16x32_bf16 v[102:105], v[176:179], v[192:195], v[102:105]
	v_mfma_f32_16x16x32_bf16 v[86:89], v[172:175], v[202:205], v[86:89]
	v_mfma_f32_16x16x32_bf16 v[86:89], v[176:179], v[206:209], v[86:89]
	v_mfma_f32_16x16x32_bf16 v[70:73], v[172:175], v[210:213], v[70:73]
	v_mfma_f32_16x16x32_bf16 v[70:73], v[176:179], v[214:217], v[70:73]
	s_barrier
; #define PG8_STAGE(bufoff, gbase, voff) do { _Pragma("unroll") for (int _i = 0; _i < 2; ++_i) \
;         __builtin_amdgcn_global_load_lds((const unsigned*)((const char*)(gbase) + (voff)[_i]), (PG8_LAS unsigned*)(lds + (bufoff) + ldsw + _i * 8192), 16, 0, 0); } while (0)
; #define PG8_LDA(dst, b, h) do { _Pragma("unroll") for (int m = 0; m < 4; ++m) _Pragma("unroll") for (int k = 0; k < 2; ++k) dst[m][k] = *(const PG8_LAS bf16x8*)(lds + PG8_SA(b, h) + aoff + m * 2048 + k * 1024); } while (0)
; #define PG8_MMA(ai, bj, At, Bt) do { __builtin_amdgcn_s_setprio(1); _Pragma("unroll") for (int m = 0; m < 4; ++m) _Pragma("unroll") for (int n = 0; n < 2; ++n) _Pragma("unroll") for (int k = 0; k < 2; ++k) \
;         acc[ai][bj][m][n] = __builtin_amdgcn_mfma_f32_16x16x32_bf16(Bt[n][k], At[m][k], acc[ai][bj][m][n], 0, 0, 0); __builtin_amdgcn_s_setprio(0); } while (0)
; #define PG8_WAIT_V(n) asm volatile("s_waitcnt vmcnt(" #n ")" ::: "memory")
; #define PG8_WAIT_L(n) asm volatile("s_waitcnt lgkmcnt(" #n ")" ::: "memory")
; #define PG8_BAR __builtin_amdgcn_s_barrier()
; #define PG8_SCHED __builtin_amdgcn_sched_barrier(0)
; template <class Epi, class Sched, bool ALIGN_EPI = false, bool SP2 = false>
; __device__ __forceinline__ void gemm_phase(PG8_LAS unsigned char* lds, const Gemm g, const Sched& S, const Epi& E) {
;     ...
;             PG8_LDA(At, 1, 1); PG8_STAGE(PG8_SB(1, 0), b3, voffB); PG8_STAGE(PG8_SB(1, 1), b3 + hstep, voffB); PG8_STAGE(PG8_SA(1, 0), a3, voffA);
;             PG8_WAIT_V(8); PG8_WAIT_L(0); PG8_BAR; PG8_MMA(1, 0, At, B0); PG8_MMA(1, 1, At, B1); PG8_BAR; PG8_SCHED;
;     ...
;         if constexpr (ALIGN_EPI) { if (wr == 0) PG8_BAR; }
	s_setprio 0
	s_add_i32 s38, s38, s75
	v_lshl_add_u64 v[218:219], v[218:219], 0, s[30:31]
	s_mov_b32 m0, s38
	ds_read_b128 v[180:183], v170 offset:49152
	ds_read_b128 v[184:187], v170 offset:50176
	ds_read_b128 v[188:191], v170 offset:51200
	ds_read_b128 v[192:195], v170 offset:52224
	ds_read_b128 v[202:205], v170 offset:53248
	ds_read_b128 v[206:209], v170 offset:54272
	ds_read_b128 v[210:213], v170 offset:55296
	ds_read_b128 v[214:217], v170 offset:56320
	global_load_lds_dwordx4 v[218:219], off
	s_add_i32 m0, s38, 0x2000
	s_add_u32 s46, s46, 0x40080
	v_lshl_add_u64 v[218:219], v[220:221], 0, s[30:31]
	s_addc_u32 s47, s47, 0
	s_add_i32 s38, s39, s75
	global_load_lds_dwordx4 v[218:219], off
	v_lshl_add_u64 v[218:219], s[46:47], 0, v[134:135]
	s_mov_b32 m0, s38
	s_nop 0
	global_load_lds_dwordx4 v[218:219], off
	v_lshl_add_u64 v[218:219], s[46:47], 0, v[130:131]
	s_add_i32 m0, s38, 0x2000
	s_nop 0
	global_load_lds_dwordx4 v[218:219], off
	v_lshl_add_u64 v[218:219], v[222:223], 0, s[30:31]
	s_mov_b32 m0, s80
	s_nop 0
	global_load_lds_dwordx4 v[218:219], off
	v_lshl_add_u64 v[218:219], v[224:225], 0, s[30:31]
	s_mov_b32 m0, s81
	s_nop 0
	global_load_lds_dwordx4 v[218:219], off
	s_waitcnt vmcnt(8)
	s_waitcnt lgkmcnt(0)
	s_setprio 1
	s_barrier
	v_mfma_f32_16x16x32_bf16 v[58:61], v[142:145], v[180:183], v[58:61]
	v_mfma_f32_16x16x32_bf16 v[58:61], v[146:149], v[184:187], v[58:61]
	v_mfma_f32_16x16x32_bf16 v[42:45], v[142:145], v[188:191], v[42:45]
	v_mfma_f32_16x16x32_bf16 v[42:45], v[146:149], v[192:195], v[42:45]
	v_mfma_f32_16x16x32_bf16 v[26:29], v[142:145], v[202:205], v[26:29]
	v_mfma_f32_16x16x32_bf16 v[26:29], v[146:149], v[206:209], v[26:29]
	v_mfma_f32_16x16x32_bf16 v[10:13], v[142:145], v[210:213], v[10:13]
	v_mfma_f32_16x16x32_bf16 v[10:13], v[146:149], v[214:217], v[10:13]
	v_mfma_f32_16x16x32_bf16 v[62:65], v[150:153], v[180:183], v[62:65]
	v_mfma_f32_16x16x32_bf16 v[62:65], v[154:157], v[184:187], v[62:65]
	v_mfma_f32_16x16x32_bf16 v[46:49], v[150:153], v[188:191], v[46:49]
	v_mfma_f32_16x16x32_bf16 v[46:49], v[154:157], v[192:195], v[46:49]
	v_mfma_f32_16x16x32_bf16 v[30:33], v[150:153], v[202:205], v[30:33]
	v_mfma_f32_16x16x32_bf16 v[30:33], v[154:157], v[206:209], v[30:33]
	v_mfma_f32_16x16x32_bf16 v[14:17], v[150:153], v[210:213], v[14:17]
	v_mfma_f32_16x16x32_bf16 v[14:17], v[154:157], v[214:217], v[14:17]
	v_mfma_f32_16x16x32_bf16 v[50:53], v[158:161], v[180:183], v[50:53]
	v_mfma_f32_16x16x32_bf16 v[50:53], v[162:165], v[184:187], v[50:53]
	v_mfma_f32_16x16x32_bf16 v[34:37], v[158:161], v[188:191], v[34:37]
	v_mfma_f32_16x16x32_bf16 v[34:37], v[162:165], v[192:195], v[34:37]
	v_mfma_f32_16x16x32_bf16 v[18:21], v[158:161], v[202:205], v[18:21]
	v_mfma_f32_16x16x32_bf16 v[18:21], v[162:165], v[206:209], v[18:21]
	v_mfma_f32_16x16x32_bf16 v[2:5], v[158:161], v[210:213], v[2:5]
	v_mfma_f32_16x16x32_bf16 v[2:5], v[162:165], v[214:217], v[2:5]
	v_mfma_f32_16x16x32_bf16 v[54:57], v[172:175], v[180:183], v[54:57]
	v_mfma_f32_16x16x32_bf16 v[54:57], v[176:179], v[184:187], v[54:57]
	v_mfma_f32_16x16x32_bf16 v[38:41], v[172:175], v[188:191], v[38:41]
	v_mfma_f32_16x16x32_bf16 v[38:41], v[176:179], v[192:195], v[38:41]
	v_mfma_f32_16x16x32_bf16 v[22:25], v[172:175], v[202:205], v[22:25]
	v_mfma_f32_16x16x32_bf16 v[22:25], v[176:179], v[206:209], v[22:25]
	v_mfma_f32_16x16x32_bf16 v[6:9], v[172:175], v[210:213], v[6:9]
	v_mfma_f32_16x16x32_bf16 v[6:9], v[176:179], v[214:217], v[6:9]
	s_barrier
	s_setprio 0
	s_add_i32 s84, s84, 2
	s_add_u32 s48, s48, 0x100
	s_addc_u32 s49, s49, 0
	s_add_u32 s53, s53, 0x100
	s_addc_u32 s69, s69, 0
	s_cmp_gt_u32 s84, 13
	s_cbranch_scc0 .LBB0_408
	s_and_b64 vcc, exec, s[64:65]
	s_cbranch_vccz .LBB0_411
	s_barrier
